# GEMM K loops: per-segment s_setprio toggling replaced by one static priority raise for waves 4-7 per unit
# baseline (speedup 1.0000x reference)
; #define PG8_STAGE(bufoff, gbase, voff) do { _Pragma("unroll") for (int _i = 0; _i < 2; ++_i) \
;         __builtin_amdgcn_global_load_lds((const unsigned*)((const char*)(gbase) + (voff)[_i]), (PG8_LAS unsigned*)(lds + (bufoff) + ldsw + _i * 8192), 16, 0, 0); } while (0)
; #define PG8_LDA(dst, b, h) do { _Pragma("unroll") for (int m = 0; m < 4; ++m) _Pragma("unroll") for (int k = 0; k < 2; ++k) dst[m][k] = *(const PG8_LAS bf16x8*)(lds + PG8_SA(b, h) + aoff + m * 2048 + k * 1024); } while (0)
; #define PG8_LDB(dst, b, h) do { _Pragma("unroll") for (int n = 0; n < 2; ++n) _Pragma("unroll") for (int k = 0; k < 2; ++k) dst[n][k] = *(const PG8_LAS bf16x8*)(lds + PG8_SB(b, h) + boff + n * 2048 + k * 1024); } while (0)
; #define PG8_MMA(ai, bj, At, Bt) do { __builtin_amdgcn_s_setprio(1); _Pragma("unroll") for (int m = 0; m < 4; ++m) _Pragma("unroll") for (int n = 0; n < 2; ++n) _Pragma("unroll") for (int k = 0; k < 2; ++k) \
;         acc[ai][bj][m][n] = __builtin_amdgcn_mfma_f32_16x16x32_bf16(Bt[n][k], At[m][k], acc[ai][bj][m][n], 0, 0, 0); __builtin_amdgcn_s_setprio(0); } while (0)
; #define PG8_WAIT_V(n) asm volatile("s_waitcnt vmcnt(" #n ")" ::: "memory")
; #define PG8_BAR __builtin_amdgcn_s_barrier()
; template <class Epi, class Sched, bool ALIGN_EPI = false, bool SP2 = false>
; __device__ __forceinline__ void gemm_phase(PG8_LAS unsigned char* lds, const Gemm g, const Sched& S, const Epi& E, const int wave0) {
;     ...
;         for (int t = 0; t < nt; t += 2) {
;             const bool last = (t == nt - 2);
;             const char* a1 = cA + (size_t)(t + 1) * kstep;
;             const char* a2 = last ? nA : cA + (size_t)(t + 2) * kstep; const char* b2 = last ? nB : cB + (size_t)(t + 2) * kstep;
;             const char* a3 = a2 + kstep; const char* b3 = b2 + kstep;
;             if (last && has_next) S.a_ready(nxt);
;             if constexpr (SP2) {
;             PG8_LDB(B0, 0, 0); PG8_LDB(B1, 0, 1); PG8_SCHED; PG8_LDA(At, 0, 0); PG8_STAGE(PG8_SA(1, 1), a1 + hstep, voffA);
;             PG8_WAIT_V(8); PG8_WAIT_L(0); PG8_BAR; PG8_MMA(0, 0, At, B0); PG8_MMA(0, 1, At, B1); PG8_BAR; PG8_SCHED;
;             PG8_LDA(At, 0, 1); PG8_STAGE(PG8_SB(0, 0), b2, voffB); PG8_STAGE(PG8_SB(0, 1), b2 + hstep, voffB); PG8_STAGE(PG8_SA(0, 0), a2, voffA);
;             PG8_WAIT_V(8); PG8_WAIT_L(0); PG8_BAR; PG8_MMA(1, 0, At, B0); PG8_MMA(1, 1, At, B1); PG8_BAR; PG8_SCHED;
.LBB0_1023:
	v_readfirstlane_b32 s98, v246
	s_cmpk_ge_u32 s98, 0x100
	s_cbranch_scc0 .Lsp_skip_1024
	s_setprio 1
.Lsp_skip_1024:
	s_add_u32 s57, s48, 0x100
	s_addc_u32 s58, s49, 0
	s_mov_b32 s59, -2
	s_waitcnt lgkmcnt(0)
	s_add_u32 s8, s10, 0x100
	s_addc_u32 s9, s11, 0
	s_add_i32 s18, 0, 0x10000
	s_cmp_eq_u32 s59, 40
	s_cselect_b32 s51, s45, s9
	s_cselect_b32 s50, s44, s8
	s_cselect_b32 s49, s47, s58
	s_cselect_b32 s48, s46, s57
	s_add_i32 s19, 0, 0x14000
	v_add_u32_e32 v140, s18, v247
	v_add_u32_e32 v156, s19, v247
	ds_read_b128 v[64:67], v140
	ds_read_b128 v[68:71], v140 offset:1024
	ds_read_b128 v[136:139], v140 offset:2048
	ds_read_b128 v[140:143], v140 offset:3072
	ds_read_b128 v[144:147], v156
	ds_read_b128 v[148:151], v156 offset:1024
	ds_read_b128 v[152:155], v156 offset:2048
	ds_read_b128 v[156:159], v156 offset:3072
	s_add_i32 m0, s33, 0xc000
	ds_read_b128 v[160:163], v245
	ds_read_b128 v[164:167], v245 offset:1024
	ds_read_b128 v[168:171], v245 offset:2048
	ds_read_b128 v[172:175], v245 offset:3072
	ds_read_b128 v[176:179], v245 offset:4096
	ds_read_b128 v[180:183], v245 offset:5120
	ds_read_b128 v[184:187], v245 offset:6144
	ds_read_b128 v[188:191], v245 offset:7168
	global_load_lds_dwordx4 v224, s[10:11]
	s_add_i32 m0, s33, 0xe000
	s_nop 0
	global_load_lds_dwordx4 v226, s[10:11]
	s_waitcnt vmcnt(8)
	s_waitcnt lgkmcnt(0)
	s_barrier
	v_mfma_f32_16x16x32_bf16 v[132:135], v[64:67], v[160:163], 0
	v_mfma_f32_16x16x32_bf16 v[128:131], v[136:139], v[160:163], 0
	v_mfma_f32_16x16x32_bf16 v[116:119], v[64:67], v[168:171], 0
	v_mfma_f32_16x16x32_bf16 v[108:111], v[136:139], v[168:171], 0
	v_mfma_f32_16x16x32_bf16 v[100:103], v[64:67], v[176:179], 0
	v_mfma_f32_16x16x32_bf16 v[92:95], v[136:139], v[176:179], 0
	v_mfma_f32_16x16x32_bf16 v[84:87], v[64:67], v[184:187], 0
	v_mfma_f32_16x16x32_bf16 v[76:79], v[136:139], v[184:187], 0
	v_mfma_f32_16x16x32_bf16 v[132:135], v[68:71], v[164:167], v[132:135]
	v_mfma_f32_16x16x32_bf16 v[128:131], v[140:143], v[164:167], v[128:131]
	v_mfma_f32_16x16x32_bf16 v[116:119], v[68:71], v[172:175], v[116:119]
	v_mfma_f32_16x16x32_bf16 v[108:111], v[140:143], v[172:175], v[108:111]
	v_mfma_f32_16x16x32_bf16 v[100:103], v[68:71], v[180:183], v[100:103]
	v_mfma_f32_16x16x32_bf16 v[92:95], v[140:143], v[180:183], v[92:95]
	v_mfma_f32_16x16x32_bf16 v[84:87], v[68:71], v[188:191], v[84:87]
	v_mfma_f32_16x16x32_bf16 v[76:79], v[140:143], v[188:191], v[76:79]
	v_mfma_f32_16x16x32_bf16 v[124:127], v[144:147], v[160:163], 0
	v_mfma_f32_16x16x32_bf16 v[120:123], v[152:155], v[160:163], 0
	v_mfma_f32_16x16x32_bf16 v[112:115], v[144:147], v[168:171], 0
	v_mfma_f32_16x16x32_bf16 v[104:107], v[152:155], v[168:171], 0
	v_mfma_f32_16x16x32_bf16 v[96:99], v[144:147], v[176:179], 0
	v_mfma_f32_16x16x32_bf16 v[88:91], v[152:155], v[176:179], 0
	v_mfma_f32_16x16x32_bf16 v[80:83], v[144:147], v[184:187], 0
	v_mfma_f32_16x16x32_bf16 v[72:75], v[152:155], v[184:187], 0
	v_mfma_f32_16x16x32_bf16 v[124:127], v[148:151], v[164:167], v[124:127]
	v_mfma_f32_16x16x32_bf16 v[120:123], v[156:159], v[164:167], v[120:123]
	v_mfma_f32_16x16x32_bf16 v[112:115], v[148:151], v[172:175], v[112:115]
	v_mfma_f32_16x16x32_bf16 v[104:107], v[156:159], v[172:175], v[104:107]
	v_mfma_f32_16x16x32_bf16 v[96:99], v[148:151], v[180:183], v[96:99]
	v_mfma_f32_16x16x32_bf16 v[88:91], v[156:159], v[180:183], v[88:91]
	v_mfma_f32_16x16x32_bf16 v[80:83], v[148:151], v[188:191], v[80:83]
	v_mfma_f32_16x16x32_bf16 v[72:75], v[156:159], v[188:191], v[72:75]
	s_barrier
	s_add_i32 s10, s18, s95
	s_mov_b32 m0, s10
	ds_read_b128 v[160:163], v245 offset:16384
	ds_read_b128 v[164:167], v245 offset:17408
	ds_read_b128 v[168:171], v245 offset:18432
	ds_read_b128 v[172:175], v245 offset:19456
	ds_read_b128 v[176:179], v245 offset:20480
	ds_read_b128 v[180:183], v245 offset:21504
	ds_read_b128 v[184:187], v245 offset:22528
	ds_read_b128 v[188:191], v245 offset:23552
	global_load_lds_dwordx4 v218, s[48:49]
	s_add_i32 m0, s10, 0x2000
	s_add_u32 s10, s48, 0xb0000
	s_addc_u32 s11, s49, 0
	s_add_i32 s18, s19, s95
	global_load_lds_dwordx4 v222, s[48:49]
	s_mov_b32 m0, s18
	s_nop 0
	global_load_lds_dwordx4 v218, s[10:11]
	s_add_i32 m0, s18, 0x2000
	s_nop 0
	global_load_lds_dwordx4 v222, s[10:11]
	s_mov_b32 m0, s33
	s_nop 0
	global_load_lds_dwordx4 v216, s[50:51]
	s_mov_b32 m0, s82
	s_nop 0
	global_load_lds_dwordx4 v220, s[50:51]
	s_waitcnt vmcnt(8)
	s_waitcnt lgkmcnt(0)
	s_barrier
	v_mfma_f32_16x16x32_bf16 v[60:63], v[64:67], v[160:163], 0
	v_mfma_f32_16x16x32_bf16 v[52:55], v[136:139], v[160:163], 0
	v_mfma_f32_16x16x32_bf16 v[44:47], v[64:67], v[168:171], 0
	v_mfma_f32_16x16x32_bf16 v[36:39], v[136:139], v[168:171], 0
	v_mfma_f32_16x16x32_bf16 v[28:31], v[64:67], v[176:179], 0
	v_mfma_f32_16x16x32_bf16 v[20:23], v[136:139], v[176:179], 0
	v_mfma_f32_16x16x32_bf16 v[12:15], v[64:67], v[184:187], 0
	v_mfma_f32_16x16x32_bf16 v[4:7], v[136:139], v[184:187], 0
	v_mfma_f32_16x16x32_bf16 v[60:63], v[68:71], v[164:167], v[60:63]
	v_mfma_f32_16x16x32_bf16 v[52:55], v[140:143], v[164:167], v[52:55]
	v_mfma_f32_16x16x32_bf16 v[44:47], v[68:71], v[172:175], v[44:47]
	v_mfma_f32_16x16x32_bf16 v[36:39], v[140:143], v[172:175], v[36:39]
	v_mfma_f32_16x16x32_bf16 v[28:31], v[68:71], v[180:183], v[28:31]
	v_mfma_f32_16x16x32_bf16 v[20:23], v[140:143], v[180:183], v[20:23]
	v_mfma_f32_16x16x32_bf16 v[12:15], v[68:71], v[188:191], v[12:15]
	v_mfma_f32_16x16x32_bf16 v[4:7], v[140:143], v[188:191], v[4:7]
	v_mfma_f32_16x16x32_bf16 v[56:59], v[144:147], v[160:163], 0
	v_mfma_f32_16x16x32_bf16 v[48:51], v[152:155], v[160:163], 0
	v_mfma_f32_16x16x32_bf16 v[40:43], v[144:147], v[168:171], 0
	v_mfma_f32_16x16x32_bf16 v[32:35], v[152:155], v[168:171], 0
	v_mfma_f32_16x16x32_bf16 v[24:27], v[144:147], v[176:179], 0
	v_mfma_f32_16x16x32_bf16 v[16:19], v[152:155], v[176:179], 0
	v_mfma_f32_16x16x32_bf16 v[8:11], v[144:147], v[184:187], 0
	v_mfma_f32_16x16x32_bf16 v[0:3], v[152:155], v[184:187], 0
	v_mfma_f32_16x16x32_bf16 v[56:59], v[148:151], v[164:167], v[56:59]
	v_mfma_f32_16x16x32_bf16 v[48:51], v[156:159], v[164:167], v[48:51]
	v_mfma_f32_16x16x32_bf16 v[40:43], v[148:151], v[172:175], v[40:43]
	v_mfma_f32_16x16x32_bf16 v[32:35], v[156:159], v[172:175], v[32:35]
	v_mfma_f32_16x16x32_bf16 v[24:27], v[148:151], v[180:183], v[24:27]
	v_mfma_f32_16x16x32_bf16 v[16:19], v[156:159], v[180:183], v[16:19]
	v_mfma_f32_16x16x32_bf16 v[8:11], v[148:151], v[188:191], v[8:11]
	v_mfma_f32_16x16x32_bf16 v[0:3], v[156:159], v[188:191], v[0:3]
	s_barrier
; #define PG8_STAGE(bufoff, gbase, voff) do { _Pragma("unroll") for (int _i = 0; _i < 2; ++_i) \
;         __builtin_amdgcn_global_load_lds((const unsigned*)((const char*)(gbase) + (voff)[_i]), (PG8_LAS unsigned*)(lds + (bufoff) + ldsw + _i * 8192), 16, 0, 0); } while (0)
; #define PG8_LDA(dst, b, h) do { _Pragma("unroll") for (int m = 0; m < 4; ++m) _Pragma("unroll") for (int k = 0; k < 2; ++k) dst[m][k] = *(const PG8_LAS bf16x8*)(lds + PG8_SA(b, h) + aoff + m * 2048 + k * 1024); } while (0)
; #define PG8_LDB(dst, b, h) do { _Pragma("unroll") for (int n = 0; n < 2; ++n) _Pragma("unroll") for (int k = 0; k < 2; ++k) dst[n][k] = *(const PG8_LAS bf16x8*)(lds + PG8_SB(b, h) + boff + n * 2048 + k * 1024); } while (0)
; #define PG8_MMA(ai, bj, At, Bt) do { __builtin_amdgcn_s_setprio(1); _Pragma("unroll") for (int m = 0; m < 4; ++m) _Pragma("unroll") for (int n = 0; n < 2; ++n) _Pragma("unroll") for (int k = 0; k < 2; ++k) \
;         acc[ai][bj][m][n] = __builtin_amdgcn_mfma_f32_16x16x32_bf16(Bt[n][k], At[m][k], acc[ai][bj][m][n], 0, 0, 0); __builtin_amdgcn_s_setprio(0); } while (0)
; #define PG8_WAIT_V(n) asm volatile("s_waitcnt vmcnt(" #n ")" ::: "memory")
; #define PG8_WAIT_L(n) asm volatile("s_waitcnt lgkmcnt(" #n ")" ::: "memory")
; #define PG8_BAR __builtin_amdgcn_s_barrier()
; #define PG8_SCHED __builtin_amdgcn_sched_barrier(0)
; template <class Epi, class Sched, bool ALIGN_EPI = false, bool SP2 = false>
; __device__ __forceinline__ void gemm_phase(PG8_LAS unsigned char* lds, const Gemm g, const Sched& S, const Epi& E, const int wave0) {
;     ...
;             PG8_LDB(B0, 1, 0); PG8_LDB(B1, 1, 1); PG8_SCHED; PG8_LDA(At, 1, 0); PG8_STAGE(PG8_SA(0, 1), a2 + hstep, voffA);
;             PG8_WAIT_V(8); PG8_WAIT_L(0); PG8_BAR; PG8_MMA(0, 0, At, B0); PG8_MMA(0, 1, At, B1); PG8_BAR; PG8_SCHED;
;             PG8_LDA(At, 1, 1); PG8_STAGE(PG8_SB(1, 0), b3, voffB); PG8_STAGE(PG8_SB(1, 1), b3 + hstep, voffB); PG8_STAGE(PG8_SA(1, 0), a3, voffA);
;             PG8_WAIT_V(8); PG8_WAIT_L(0); PG8_BAR; PG8_MMA(1, 0, At, B0); PG8_MMA(1, 1, At, B1); PG8_BAR; PG8_SCHED;
	s_add_i32 s18, 0, 0x18000
	s_add_i32 s19, 0, 0x1c000
	v_add_u32_e32 v140, s18, v247
	v_add_u32_e32 v156, s19, v247
	ds_read_b128 v[64:67], v140
	ds_read_b128 v[68:71], v140 offset:1024
	ds_read_b128 v[136:139], v140 offset:2048
	ds_read_b128 v[140:143], v140 offset:3072
	ds_read_b128 v[144:147], v156
	ds_read_b128 v[148:151], v156 offset:1024
	ds_read_b128 v[152:155], v156 offset:2048
	ds_read_b128 v[156:159], v156 offset:3072
	s_add_u32 s10, s50, 0xb0000
	s_addc_u32 s11, s51, 0
	s_mov_b32 m0, s16
	ds_read_b128 v[160:163], v245 offset:32768
	ds_read_b128 v[164:167], v245 offset:33792
	ds_read_b128 v[168:171], v245 offset:34816
	ds_read_b128 v[172:175], v245 offset:35840
	ds_read_b128 v[176:179], v245 offset:36864
	ds_read_b128 v[180:183], v245 offset:37888
	ds_read_b128 v[184:187], v245 offset:38912
	ds_read_b128 v[188:191], v245 offset:39936
	global_load_lds_dwordx4 v216, s[10:11]
	s_mov_b32 m0, s83
	s_nop 0
	global_load_lds_dwordx4 v220, s[10:11]
	s_waitcnt vmcnt(8)
	s_waitcnt lgkmcnt(0)
	s_barrier
	v_mfma_f32_16x16x32_bf16 v[132:135], v[64:67], v[160:163], v[132:135]
	v_mfma_f32_16x16x32_bf16 v[128:131], v[136:139], v[160:163], v[128:131]
	v_mfma_f32_16x16x32_bf16 v[116:119], v[64:67], v[168:171], v[116:119]
	v_mfma_f32_16x16x32_bf16 v[108:111], v[136:139], v[168:171], v[108:111]
	v_mfma_f32_16x16x32_bf16 v[100:103], v[64:67], v[176:179], v[100:103]
	v_mfma_f32_16x16x32_bf16 v[92:95], v[136:139], v[176:179], v[92:95]
	v_mfma_f32_16x16x32_bf16 v[84:87], v[64:67], v[184:187], v[84:87]
	v_mfma_f32_16x16x32_bf16 v[76:79], v[136:139], v[184:187], v[76:79]
	v_mfma_f32_16x16x32_bf16 v[132:135], v[68:71], v[164:167], v[132:135]
	v_mfma_f32_16x16x32_bf16 v[128:131], v[140:143], v[164:167], v[128:131]
	v_mfma_f32_16x16x32_bf16 v[116:119], v[68:71], v[172:175], v[116:119]
	v_mfma_f32_16x16x32_bf16 v[108:111], v[140:143], v[172:175], v[108:111]
	v_mfma_f32_16x16x32_bf16 v[100:103], v[68:71], v[180:183], v[100:103]
	v_mfma_f32_16x16x32_bf16 v[92:95], v[140:143], v[180:183], v[92:95]
	v_mfma_f32_16x16x32_bf16 v[84:87], v[68:71], v[188:191], v[84:87]
	v_mfma_f32_16x16x32_bf16 v[76:79], v[140:143], v[188:191], v[76:79]
	v_mfma_f32_16x16x32_bf16 v[124:127], v[144:147], v[160:163], v[124:127]
	v_mfma_f32_16x16x32_bf16 v[120:123], v[152:155], v[160:163], v[120:123]
	v_mfma_f32_16x16x32_bf16 v[112:115], v[144:147], v[168:171], v[112:115]
	v_mfma_f32_16x16x32_bf16 v[104:107], v[152:155], v[168:171], v[104:107]
	v_mfma_f32_16x16x32_bf16 v[96:99], v[144:147], v[176:179], v[96:99]
	v_mfma_f32_16x16x32_bf16 v[88:91], v[152:155], v[176:179], v[88:91]
	v_mfma_f32_16x16x32_bf16 v[80:83], v[144:147], v[184:187], v[80:83]
	v_mfma_f32_16x16x32_bf16 v[72:75], v[152:155], v[184:187], v[72:75]
	v_mfma_f32_16x16x32_bf16 v[124:127], v[148:151], v[164:167], v[124:127]
	v_mfma_f32_16x16x32_bf16 v[120:123], v[156:159], v[164:167], v[120:123]
	v_mfma_f32_16x16x32_bf16 v[112:115], v[148:151], v[172:175], v[112:115]
	v_mfma_f32_16x16x32_bf16 v[104:107], v[156:159], v[172:175], v[104:107]
	v_mfma_f32_16x16x32_bf16 v[96:99], v[148:151], v[180:183], v[96:99]
	v_mfma_f32_16x16x32_bf16 v[88:91], v[156:159], v[180:183], v[88:91]
	v_mfma_f32_16x16x32_bf16 v[80:83], v[148:151], v[188:191], v[80:83]
	v_mfma_f32_16x16x32_bf16 v[72:75], v[156:159], v[188:191], v[72:75]
	s_barrier
	s_add_i32 s10, s18, s95
	s_add_i32 m0, s10, 0xffffff80
	ds_read_b128 v[160:163], v245 offset:49152
	ds_read_b128 v[164:167], v245 offset:50176
	ds_read_b128 v[168:171], v245 offset:51200
	ds_read_b128 v[172:175], v245 offset:52224
	ds_read_b128 v[176:179], v245 offset:53248
	ds_read_b128 v[180:183], v245 offset:54272
	ds_read_b128 v[184:187], v245 offset:55296
	ds_read_b128 v[188:191], v245 offset:56320
	global_load_lds_dwordx4 v218, s[48:49] offset:128
	s_add_i32 m0, s10, 0x1f80
	s_add_u32 s10, s48, 0xb0080
	s_addc_u32 s11, s49, 0
	s_add_i32 s18, s19, s95
	global_load_lds_dwordx4 v222, s[48:49] offset:128
	s_mov_b32 m0, s18
	s_nop 0
	global_load_lds_dwordx4 v218, s[10:11]
	s_add_i32 m0, s18, 0x2000
	s_nop 0
	global_load_lds_dwordx4 v222, s[10:11]
	s_add_i32 m0, s17, 0xffffff80
	s_nop 0
	global_load_lds_dwordx4 v216, s[50:51] offset:128
	s_add_i32 m0, s23, 0xffffff80
	s_nop 0
	global_load_lds_dwordx4 v220, s[50:51] offset:128
	s_waitcnt vmcnt(8)
	s_waitcnt lgkmcnt(0)
	s_barrier
	v_mfma_f32_16x16x32_bf16 v[60:63], v[64:67], v[160:163], v[60:63]
	v_mfma_f32_16x16x32_bf16 v[52:55], v[136:139], v[160:163], v[52:55]
	v_mfma_f32_16x16x32_bf16 v[44:47], v[64:67], v[168:171], v[44:47]
	v_mfma_f32_16x16x32_bf16 v[36:39], v[136:139], v[168:171], v[36:39]
	v_mfma_f32_16x16x32_bf16 v[28:31], v[64:67], v[176:179], v[28:31]
	v_mfma_f32_16x16x32_bf16 v[20:23], v[136:139], v[176:179], v[20:23]
	v_mfma_f32_16x16x32_bf16 v[12:15], v[64:67], v[184:187], v[12:15]
	v_mfma_f32_16x16x32_bf16 v[4:7], v[136:139], v[184:187], v[4:7]
	v_mfma_f32_16x16x32_bf16 v[60:63], v[68:71], v[164:167], v[60:63]
	v_mfma_f32_16x16x32_bf16 v[52:55], v[140:143], v[164:167], v[52:55]
	v_mfma_f32_16x16x32_bf16 v[44:47], v[68:71], v[172:175], v[44:47]
	v_mfma_f32_16x16x32_bf16 v[36:39], v[140:143], v[172:175], v[36:39]
	v_mfma_f32_16x16x32_bf16 v[28:31], v[68:71], v[180:183], v[28:31]
	v_mfma_f32_16x16x32_bf16 v[20:23], v[140:143], v[180:183], v[20:23]
	v_mfma_f32_16x16x32_bf16 v[12:15], v[68:71], v[188:191], v[12:15]
	v_mfma_f32_16x16x32_bf16 v[4:7], v[140:143], v[188:191], v[4:7]
	v_mfma_f32_16x16x32_bf16 v[56:59], v[144:147], v[160:163], v[56:59]
	v_mfma_f32_16x16x32_bf16 v[48:51], v[152:155], v[160:163], v[48:51]
	v_mfma_f32_16x16x32_bf16 v[40:43], v[144:147], v[168:171], v[40:43]
	v_mfma_f32_16x16x32_bf16 v[32:35], v[152:155], v[168:171], v[32:35]
	v_mfma_f32_16x16x32_bf16 v[24:27], v[144:147], v[176:179], v[24:27]
	v_mfma_f32_16x16x32_bf16 v[16:19], v[152:155], v[176:179], v[16:19]
	v_mfma_f32_16x16x32_bf16 v[8:11], v[144:147], v[184:187], v[8:11]
	v_mfma_f32_16x16x32_bf16 v[0:3], v[152:155], v[184:187], v[0:3]
	v_mfma_f32_16x16x32_bf16 v[56:59], v[148:151], v[164:167], v[56:59]
	v_mfma_f32_16x16x32_bf16 v[48:51], v[156:159], v[164:167], v[48:51]
	v_mfma_f32_16x16x32_bf16 v[40:43], v[148:151], v[172:175], v[40:43]
	v_mfma_f32_16x16x32_bf16 v[32:35], v[156:159], v[172:175], v[32:35]
	v_mfma_f32_16x16x32_bf16 v[24:27], v[148:151], v[180:183], v[24:27]
	v_mfma_f32_16x16x32_bf16 v[16:19], v[156:159], v[180:183], v[16:19]
	v_mfma_f32_16x16x32_bf16 v[8:11], v[148:151], v[188:191], v[8:11]
	v_mfma_f32_16x16x32_bf16 v[0:3], v[156:159], v[188:191], v[0:3]
	s_barrier
	s_add_i32 s59, s59, 2
	s_add_u32 s57, s57, 0x100
	s_addc_u32 s58, s58, 0
	s_cmp_gt_u32 s59, 41
	s_mov_b64 s[10:11], s[8:9]
; #define PG8_STAGE(bufoff, gbase, voff) do { _Pragma("unroll") for (int _i = 0; _i < 2; ++_i) \
;         __builtin_amdgcn_global_load_lds((const unsigned*)((const char*)(gbase) + (voff)[_i]), (PG8_LAS unsigned*)(lds + (bufoff) + ldsw + _i * 8192), 16, 0, 0); } while (0)
; #define PG8_LDA(dst, b, h) do { _Pragma("unroll") for (int m = 0; m < 4; ++m) _Pragma("unroll") for (int k = 0; k < 2; ++k) dst[m][k] = *(const PG8_LAS bf16x8*)(lds + PG8_SA(b, h) + aoff + m * 2048 + k * 1024); } while (0)
; #define PG8_LDB(dst, b, h) do { _Pragma("unroll") for (int n = 0; n < 2; ++n) _Pragma("unroll") for (int k = 0; k < 2; ++k) dst[n][k] = *(const PG8_LAS bf16x8*)(lds + PG8_SB(b, h) + boff + n * 2048 + k * 1024); } while (0)
; #define PG8_MMA(ai, bj, At, Bt) do { __builtin_amdgcn_s_setprio(1); _Pragma("unroll") for (int m = 0; m < 4; ++m) _Pragma("unroll") for (int n = 0; n < 2; ++n) _Pragma("unroll") for (int k = 0; k < 2; ++k) \
;         acc[ai][bj][m][n] = __builtin_amdgcn_mfma_f32_16x16x32_bf16(Bt[n][k], At[m][k], acc[ai][bj][m][n], 0, 0, 0); __builtin_amdgcn_s_setprio(0); } while (0)
; #define PG8_WAIT_V(n) asm volatile("s_waitcnt vmcnt(" #n ")" ::: "memory")
; #define PG8_BAR __builtin_amdgcn_s_barrier()
; template <class Epi, class Sched, bool ALIGN_EPI = false, bool SP2 = false>
; __device__ __forceinline__ void gemm_phase(PG8_LAS unsigned char* lds, const Gemm g, const Sched& S, const Epi& E, const int wave0) {
;     ...
;         for (int t = 0; t < nt; t += 2) {
;             const bool last = (t == nt - 2);
;             const char* a1 = cA + (size_t)(t + 1) * kstep;
;             const char* a2 = last ? nA : cA + (size_t)(t + 2) * kstep; const char* b2 = last ? nB : cB + (size_t)(t + 2) * kstep;
;             const char* a3 = a2 + kstep; const char* b3 = b2 + kstep;
;             if (last && has_next) S.a_ready(nxt);
;             if constexpr (SP2) {
;             PG8_LDB(B0, 0, 0); PG8_LDB(B1, 0, 1); PG8_SCHED; PG8_LDA(At, 0, 0); PG8_STAGE(PG8_SA(1, 1), a1 + hstep, voffA);
;             PG8_WAIT_V(8); PG8_WAIT_L(0); PG8_BAR; PG8_MMA(0, 0, At, B0); PG8_MMA(0, 1, At, B1); PG8_BAR; PG8_SCHED;
;             PG8_LDA(At, 0, 1); PG8_STAGE(PG8_SB(0, 0), b2, voffB); PG8_STAGE(PG8_SB(0, 1), b2 + hstep, voffB); PG8_STAGE(PG8_SA(0, 0), a2, voffA);
;             PG8_WAIT_V(8); PG8_WAIT_L(0); PG8_BAR; PG8_MMA(1, 0, At, B0); PG8_MMA(1, 1, At, B1); PG8_BAR; PG8_SCHED;
.LBB0_1024:
	s_add_u32 s8, s10, 0x100
	s_addc_u32 s9, s11, 0
	s_add_i32 s18, 0, 0x10000
	s_cmp_eq_u32 s59, 40
	s_cselect_b32 s51, s45, s9
	s_cselect_b32 s50, s44, s8
	s_cselect_b32 s49, s47, s58
	s_cselect_b32 s48, s46, s57
	s_add_i32 s19, 0, 0x14000
	v_add_u32_e32 v140, s18, v247
	v_add_u32_e32 v156, s19, v247
	ds_read_b128 v[64:67], v140
	ds_read_b128 v[68:71], v140 offset:1024
	ds_read_b128 v[136:139], v140 offset:2048
	ds_read_b128 v[140:143], v140 offset:3072
	ds_read_b128 v[144:147], v156
	ds_read_b128 v[148:151], v156 offset:1024
	ds_read_b128 v[152:155], v156 offset:2048
	ds_read_b128 v[156:159], v156 offset:3072
	s_add_i32 m0, s33, 0xc000
	ds_read_b128 v[160:163], v245
	ds_read_b128 v[164:167], v245 offset:1024
	ds_read_b128 v[168:171], v245 offset:2048
	ds_read_b128 v[172:175], v245 offset:3072
	ds_read_b128 v[176:179], v245 offset:4096
	ds_read_b128 v[180:183], v245 offset:5120
	ds_read_b128 v[184:187], v245 offset:6144
	ds_read_b128 v[188:191], v245 offset:7168
	global_load_lds_dwordx4 v224, s[10:11]
	s_add_i32 m0, s33, 0xe000
	s_nop 0
	global_load_lds_dwordx4 v226, s[10:11]
	s_waitcnt vmcnt(8)
	s_waitcnt lgkmcnt(0)
	s_barrier
	v_mfma_f32_16x16x32_bf16 v[132:135], v[64:67], v[160:163], v[132:135]
	v_mfma_f32_16x16x32_bf16 v[128:131], v[136:139], v[160:163], v[128:131]
	v_mfma_f32_16x16x32_bf16 v[116:119], v[64:67], v[168:171], v[116:119]
	v_mfma_f32_16x16x32_bf16 v[108:111], v[136:139], v[168:171], v[108:111]
	v_mfma_f32_16x16x32_bf16 v[100:103], v[64:67], v[176:179], v[100:103]
	v_mfma_f32_16x16x32_bf16 v[92:95], v[136:139], v[176:179], v[92:95]
	v_mfma_f32_16x16x32_bf16 v[84:87], v[64:67], v[184:187], v[84:87]
	v_mfma_f32_16x16x32_bf16 v[76:79], v[136:139], v[184:187], v[76:79]
	v_mfma_f32_16x16x32_bf16 v[132:135], v[68:71], v[164:167], v[132:135]
	v_mfma_f32_16x16x32_bf16 v[128:131], v[140:143], v[164:167], v[128:131]
	v_mfma_f32_16x16x32_bf16 v[116:119], v[68:71], v[172:175], v[116:119]
	v_mfma_f32_16x16x32_bf16 v[108:111], v[140:143], v[172:175], v[108:111]
	v_mfma_f32_16x16x32_bf16 v[100:103], v[68:71], v[180:183], v[100:103]
	v_mfma_f32_16x16x32_bf16 v[92:95], v[140:143], v[180:183], v[92:95]
	v_mfma_f32_16x16x32_bf16 v[84:87], v[68:71], v[188:191], v[84:87]
	v_mfma_f32_16x16x32_bf16 v[76:79], v[140:143], v[188:191], v[76:79]
	v_mfma_f32_16x16x32_bf16 v[124:127], v[144:147], v[160:163], v[124:127]
	v_mfma_f32_16x16x32_bf16 v[120:123], v[152:155], v[160:163], v[120:123]
	v_mfma_f32_16x16x32_bf16 v[112:115], v[144:147], v[168:171], v[112:115]
	v_mfma_f32_16x16x32_bf16 v[104:107], v[152:155], v[168:171], v[104:107]
	v_mfma_f32_16x16x32_bf16 v[96:99], v[144:147], v[176:179], v[96:99]
	v_mfma_f32_16x16x32_bf16 v[88:91], v[152:155], v[176:179], v[88:91]
	v_mfma_f32_16x16x32_bf16 v[80:83], v[144:147], v[184:187], v[80:83]
	v_mfma_f32_16x16x32_bf16 v[72:75], v[152:155], v[184:187], v[72:75]
	v_mfma_f32_16x16x32_bf16 v[124:127], v[148:151], v[164:167], v[124:127]
	v_mfma_f32_16x16x32_bf16 v[120:123], v[156:159], v[164:167], v[120:123]
	v_mfma_f32_16x16x32_bf16 v[112:115], v[148:151], v[172:175], v[112:115]
	v_mfma_f32_16x16x32_bf16 v[104:107], v[156:159], v[172:175], v[104:107]
	v_mfma_f32_16x16x32_bf16 v[96:99], v[148:151], v[180:183], v[96:99]
	v_mfma_f32_16x16x32_bf16 v[88:91], v[156:159], v[180:183], v[88:91]
	v_mfma_f32_16x16x32_bf16 v[80:83], v[148:151], v[188:191], v[80:83]
	v_mfma_f32_16x16x32_bf16 v[72:75], v[156:159], v[188:191], v[72:75]
	s_barrier
	s_add_i32 s10, s18, s95
	s_mov_b32 m0, s10
	ds_read_b128 v[160:163], v245 offset:16384
	ds_read_b128 v[164:167], v245 offset:17408
	ds_read_b128 v[168:171], v245 offset:18432
	ds_read_b128 v[172:175], v245 offset:19456
	ds_read_b128 v[176:179], v245 offset:20480
	ds_read_b128 v[180:183], v245 offset:21504
	ds_read_b128 v[184:187], v245 offset:22528
	ds_read_b128 v[188:191], v245 offset:23552
	global_load_lds_dwordx4 v218, s[48:49]
	s_add_i32 m0, s10, 0x2000
	s_add_u32 s10, s48, 0xb0000
	s_addc_u32 s11, s49, 0
	s_add_i32 s18, s19, s95
	global_load_lds_dwordx4 v222, s[48:49]
	s_mov_b32 m0, s18
	s_nop 0
	global_load_lds_dwordx4 v218, s[10:11]
	s_add_i32 m0, s18, 0x2000
	s_nop 0
	global_load_lds_dwordx4 v222, s[10:11]
	s_mov_b32 m0, s33
	s_nop 0
	global_load_lds_dwordx4 v216, s[50:51]
	s_mov_b32 m0, s82
	s_nop 0
	global_load_lds_dwordx4 v220, s[50:51]
	s_waitcnt vmcnt(8)
	s_waitcnt lgkmcnt(0)
	s_barrier
	v_mfma_f32_16x16x32_bf16 v[60:63], v[64:67], v[160:163], v[60:63]
	v_mfma_f32_16x16x32_bf16 v[52:55], v[136:139], v[160:163], v[52:55]
	v_mfma_f32_16x16x32_bf16 v[44:47], v[64:67], v[168:171], v[44:47]
	v_mfma_f32_16x16x32_bf16 v[36:39], v[136:139], v[168:171], v[36:39]
	v_mfma_f32_16x16x32_bf16 v[28:31], v[64:67], v[176:179], v[28:31]
	v_mfma_f32_16x16x32_bf16 v[20:23], v[136:139], v[176:179], v[20:23]
	v_mfma_f32_16x16x32_bf16 v[12:15], v[64:67], v[184:187], v[12:15]
	v_mfma_f32_16x16x32_bf16 v[4:7], v[136:139], v[184:187], v[4:7]
	v_mfma_f32_16x16x32_bf16 v[60:63], v[68:71], v[164:167], v[60:63]
	v_mfma_f32_16x16x32_bf16 v[52:55], v[140:143], v[164:167], v[52:55]
	v_mfma_f32_16x16x32_bf16 v[44:47], v[68:71], v[172:175], v[44:47]
	v_mfma_f32_16x16x32_bf16 v[36:39], v[140:143], v[172:175], v[36:39]
	v_mfma_f32_16x16x32_bf16 v[28:31], v[68:71], v[180:183], v[28:31]
	v_mfma_f32_16x16x32_bf16 v[20:23], v[140:143], v[180:183], v[20:23]
	v_mfma_f32_16x16x32_bf16 v[12:15], v[68:71], v[188:191], v[12:15]
	v_mfma_f32_16x16x32_bf16 v[4:7], v[140:143], v[188:191], v[4:7]
	v_mfma_f32_16x16x32_bf16 v[56:59], v[144:147], v[160:163], v[56:59]
	v_mfma_f32_16x16x32_bf16 v[48:51], v[152:155], v[160:163], v[48:51]
	v_mfma_f32_16x16x32_bf16 v[40:43], v[144:147], v[168:171], v[40:43]
	v_mfma_f32_16x16x32_bf16 v[32:35], v[152:155], v[168:171], v[32:35]
	v_mfma_f32_16x16x32_bf16 v[24:27], v[144:147], v[176:179], v[24:27]
	v_mfma_f32_16x16x32_bf16 v[16:19], v[152:155], v[176:179], v[16:19]
	v_mfma_f32_16x16x32_bf16 v[8:11], v[144:147], v[184:187], v[8:11]
	v_mfma_f32_16x16x32_bf16 v[0:3], v[152:155], v[184:187], v[0:3]
	v_mfma_f32_16x16x32_bf16 v[56:59], v[148:151], v[164:167], v[56:59]
	v_mfma_f32_16x16x32_bf16 v[48:51], v[156:159], v[164:167], v[48:51]
	v_mfma_f32_16x16x32_bf16 v[40:43], v[148:151], v[172:175], v[40:43]
	v_mfma_f32_16x16x32_bf16 v[32:35], v[156:159], v[172:175], v[32:35]
	v_mfma_f32_16x16x32_bf16 v[24:27], v[148:151], v[180:183], v[24:27]
	v_mfma_f32_16x16x32_bf16 v[16:19], v[156:159], v[180:183], v[16:19]
	v_mfma_f32_16x16x32_bf16 v[8:11], v[148:151], v[188:191], v[8:11]
	v_mfma_f32_16x16x32_bf16 v[0:3], v[156:159], v[188:191], v[0:3]
	s_barrier
; #define PG8_STAGE(bufoff, gbase, voff) do { _Pragma("unroll") for (int _i = 0; _i < 2; ++_i) \
;         __builtin_amdgcn_global_load_lds((const unsigned*)((const char*)(gbase) + (voff)[_i]), (PG8_LAS unsigned*)(lds + (bufoff) + ldsw + _i * 8192), 16, 0, 0); } while (0)
; #define PG8_LDA(dst, b, h) do { _Pragma("unroll") for (int m = 0; m < 4; ++m) _Pragma("unroll") for (int k = 0; k < 2; ++k) dst[m][k] = *(const PG8_LAS bf16x8*)(lds + PG8_SA(b, h) + aoff + m * 2048 + k * 1024); } while (0)
; #define PG8_LDB(dst, b, h) do { _Pragma("unroll") for (int n = 0; n < 2; ++n) _Pragma("unroll") for (int k = 0; k < 2; ++k) dst[n][k] = *(const PG8_LAS bf16x8*)(lds + PG8_SB(b, h) + boff + n * 2048 + k * 1024); } while (0)
; #define PG8_MMA(ai, bj, At, Bt) do { __builtin_amdgcn_s_setprio(1); _Pragma("unroll") for (int m = 0; m < 4; ++m) _Pragma("unroll") for (int n = 0; n < 2; ++n) _Pragma("unroll") for (int k = 0; k < 2; ++k) \
;         acc[ai][bj][m][n] = __builtin_amdgcn_mfma_f32_16x16x32_bf16(Bt[n][k], At[m][k], acc[ai][bj][m][n], 0, 0, 0); __builtin_amdgcn_s_setprio(0); } while (0)
; #define PG8_WAIT_V(n) asm volatile("s_waitcnt vmcnt(" #n ")" ::: "memory")
; #define PG8_WAIT_L(n) asm volatile("s_waitcnt lgkmcnt(" #n ")" ::: "memory")
; #define PG8_BAR __builtin_amdgcn_s_barrier()
; #define PG8_SCHED __builtin_amdgcn_sched_barrier(0)
; template <class Epi, class Sched, bool ALIGN_EPI = false, bool SP2 = false>
; __device__ __forceinline__ void gemm_phase(PG8_LAS unsigned char* lds, const Gemm g, const Sched& S, const Epi& E, const int wave0) {
;     ...
;             PG8_LDB(B0, 1, 0); PG8_LDB(B1, 1, 1); PG8_SCHED; PG8_LDA(At, 1, 0); PG8_STAGE(PG8_SA(0, 1), a2 + hstep, voffA);
;             PG8_WAIT_V(8); PG8_WAIT_L(0); PG8_BAR; PG8_MMA(0, 0, At, B0); PG8_MMA(0, 1, At, B1); PG8_BAR; PG8_SCHED;
;             PG8_LDA(At, 1, 1); PG8_STAGE(PG8_SB(1, 0), b3, voffB); PG8_STAGE(PG8_SB(1, 1), b3 + hstep, voffB); PG8_STAGE(PG8_SA(1, 0), a3, voffA);
;             PG8_WAIT_V(8); PG8_WAIT_L(0); PG8_BAR; PG8_MMA(1, 0, At, B0); PG8_MMA(1, 1, At, B1); PG8_BAR; PG8_SCHED;
;     ...
;         if constexpr (ALIGN_EPI) { if (wr == 0) PG8_BAR; }
	s_add_i32 s18, 0, 0x18000
	s_add_i32 s19, 0, 0x1c000
	v_add_u32_e32 v140, s18, v247
	v_add_u32_e32 v156, s19, v247
	ds_read_b128 v[64:67], v140
	ds_read_b128 v[68:71], v140 offset:1024
	ds_read_b128 v[136:139], v140 offset:2048
	ds_read_b128 v[140:143], v140 offset:3072
	ds_read_b128 v[144:147], v156
	ds_read_b128 v[148:151], v156 offset:1024
	ds_read_b128 v[152:155], v156 offset:2048
	ds_read_b128 v[156:159], v156 offset:3072
	s_add_u32 s10, s50, 0xb0000
	s_addc_u32 s11, s51, 0
	s_mov_b32 m0, s16
	ds_read_b128 v[160:163], v245 offset:32768
	ds_read_b128 v[164:167], v245 offset:33792
	ds_read_b128 v[168:171], v245 offset:34816
	ds_read_b128 v[172:175], v245 offset:35840
	ds_read_b128 v[176:179], v245 offset:36864
	ds_read_b128 v[180:183], v245 offset:37888
	ds_read_b128 v[184:187], v245 offset:38912
	ds_read_b128 v[188:191], v245 offset:39936
	global_load_lds_dwordx4 v216, s[10:11]
	s_mov_b32 m0, s83
	s_nop 0
	global_load_lds_dwordx4 v220, s[10:11]
	s_waitcnt vmcnt(8)
	s_waitcnt lgkmcnt(0)
	s_barrier
	v_mfma_f32_16x16x32_bf16 v[132:135], v[64:67], v[160:163], v[132:135]
	v_mfma_f32_16x16x32_bf16 v[128:131], v[136:139], v[160:163], v[128:131]
	v_mfma_f32_16x16x32_bf16 v[116:119], v[64:67], v[168:171], v[116:119]
	v_mfma_f32_16x16x32_bf16 v[108:111], v[136:139], v[168:171], v[108:111]
	v_mfma_f32_16x16x32_bf16 v[100:103], v[64:67], v[176:179], v[100:103]
	v_mfma_f32_16x16x32_bf16 v[92:95], v[136:139], v[176:179], v[92:95]
	v_mfma_f32_16x16x32_bf16 v[84:87], v[64:67], v[184:187], v[84:87]
	v_mfma_f32_16x16x32_bf16 v[76:79], v[136:139], v[184:187], v[76:79]
	v_mfma_f32_16x16x32_bf16 v[132:135], v[68:71], v[164:167], v[132:135]
	v_mfma_f32_16x16x32_bf16 v[128:131], v[140:143], v[164:167], v[128:131]
	v_mfma_f32_16x16x32_bf16 v[116:119], v[68:71], v[172:175], v[116:119]
	v_mfma_f32_16x16x32_bf16 v[108:111], v[140:143], v[172:175], v[108:111]
	v_mfma_f32_16x16x32_bf16 v[100:103], v[68:71], v[180:183], v[100:103]
	v_mfma_f32_16x16x32_bf16 v[92:95], v[140:143], v[180:183], v[92:95]
	v_mfma_f32_16x16x32_bf16 v[84:87], v[68:71], v[188:191], v[84:87]
	v_mfma_f32_16x16x32_bf16 v[76:79], v[140:143], v[188:191], v[76:79]
	v_mfma_f32_16x16x32_bf16 v[124:127], v[144:147], v[160:163], v[124:127]
	v_mfma_f32_16x16x32_bf16 v[120:123], v[152:155], v[160:163], v[120:123]
	v_mfma_f32_16x16x32_bf16 v[112:115], v[144:147], v[168:171], v[112:115]
	v_mfma_f32_16x16x32_bf16 v[104:107], v[152:155], v[168:171], v[104:107]
	v_mfma_f32_16x16x32_bf16 v[96:99], v[144:147], v[176:179], v[96:99]
	v_mfma_f32_16x16x32_bf16 v[88:91], v[152:155], v[176:179], v[88:91]
	v_mfma_f32_16x16x32_bf16 v[80:83], v[144:147], v[184:187], v[80:83]
	v_mfma_f32_16x16x32_bf16 v[72:75], v[152:155], v[184:187], v[72:75]
	v_mfma_f32_16x16x32_bf16 v[124:127], v[148:151], v[164:167], v[124:127]
	v_mfma_f32_16x16x32_bf16 v[120:123], v[156:159], v[164:167], v[120:123]
	v_mfma_f32_16x16x32_bf16 v[112:115], v[148:151], v[172:175], v[112:115]
	v_mfma_f32_16x16x32_bf16 v[104:107], v[156:159], v[172:175], v[104:107]
	v_mfma_f32_16x16x32_bf16 v[96:99], v[148:151], v[180:183], v[96:99]
	v_mfma_f32_16x16x32_bf16 v[88:91], v[156:159], v[180:183], v[88:91]
	v_mfma_f32_16x16x32_bf16 v[80:83], v[148:151], v[188:191], v[80:83]
	v_mfma_f32_16x16x32_bf16 v[72:75], v[156:159], v[188:191], v[72:75]
	s_barrier
	s_add_i32 s10, s18, s95
	s_add_i32 m0, s10, 0xffffff80
	ds_read_b128 v[160:163], v245 offset:49152
	ds_read_b128 v[164:167], v245 offset:50176
	ds_read_b128 v[168:171], v245 offset:51200
	ds_read_b128 v[172:175], v245 offset:52224
	ds_read_b128 v[176:179], v245 offset:53248
	ds_read_b128 v[180:183], v245 offset:54272
	ds_read_b128 v[184:187], v245 offset:55296
	ds_read_b128 v[188:191], v245 offset:56320
	global_load_lds_dwordx4 v218, s[48:49] offset:128
	s_add_i32 m0, s10, 0x1f80
	s_add_u32 s10, s48, 0xb0080
	s_addc_u32 s11, s49, 0
	s_add_i32 s18, s19, s95
	global_load_lds_dwordx4 v222, s[48:49] offset:128
	s_mov_b32 m0, s18
	s_nop 0
	global_load_lds_dwordx4 v218, s[10:11]
	s_add_i32 m0, s18, 0x2000
	s_nop 0
	global_load_lds_dwordx4 v222, s[10:11]
	s_add_i32 m0, s17, 0xffffff80
	s_nop 0
	global_load_lds_dwordx4 v216, s[50:51] offset:128
	s_add_i32 m0, s23, 0xffffff80
	s_nop 0
	global_load_lds_dwordx4 v220, s[50:51] offset:128
	s_waitcnt vmcnt(8)
	s_waitcnt lgkmcnt(0)
	s_barrier
	v_mfma_f32_16x16x32_bf16 v[60:63], v[64:67], v[160:163], v[60:63]
	v_mfma_f32_16x16x32_bf16 v[52:55], v[136:139], v[160:163], v[52:55]
	v_mfma_f32_16x16x32_bf16 v[44:47], v[64:67], v[168:171], v[44:47]
	v_mfma_f32_16x16x32_bf16 v[36:39], v[136:139], v[168:171], v[36:39]
	v_mfma_f32_16x16x32_bf16 v[28:31], v[64:67], v[176:179], v[28:31]
	v_mfma_f32_16x16x32_bf16 v[20:23], v[136:139], v[176:179], v[20:23]
	v_mfma_f32_16x16x32_bf16 v[12:15], v[64:67], v[184:187], v[12:15]
	v_mfma_f32_16x16x32_bf16 v[4:7], v[136:139], v[184:187], v[4:7]
	v_mfma_f32_16x16x32_bf16 v[60:63], v[68:71], v[164:167], v[60:63]
	v_mfma_f32_16x16x32_bf16 v[52:55], v[140:143], v[164:167], v[52:55]
	v_mfma_f32_16x16x32_bf16 v[44:47], v[68:71], v[172:175], v[44:47]
	v_mfma_f32_16x16x32_bf16 v[36:39], v[140:143], v[172:175], v[36:39]
	v_mfma_f32_16x16x32_bf16 v[28:31], v[68:71], v[180:183], v[28:31]
	v_mfma_f32_16x16x32_bf16 v[20:23], v[140:143], v[180:183], v[20:23]
	v_mfma_f32_16x16x32_bf16 v[12:15], v[68:71], v[188:191], v[12:15]
	v_mfma_f32_16x16x32_bf16 v[4:7], v[140:143], v[188:191], v[4:7]
	v_mfma_f32_16x16x32_bf16 v[56:59], v[144:147], v[160:163], v[56:59]
	v_mfma_f32_16x16x32_bf16 v[48:51], v[152:155], v[160:163], v[48:51]
	v_mfma_f32_16x16x32_bf16 v[40:43], v[144:147], v[168:171], v[40:43]
	v_mfma_f32_16x16x32_bf16 v[32:35], v[152:155], v[168:171], v[32:35]
	v_mfma_f32_16x16x32_bf16 v[24:27], v[144:147], v[176:179], v[24:27]
	v_mfma_f32_16x16x32_bf16 v[16:19], v[152:155], v[176:179], v[16:19]
	v_mfma_f32_16x16x32_bf16 v[8:11], v[144:147], v[184:187], v[8:11]
	v_mfma_f32_16x16x32_bf16 v[0:3], v[152:155], v[184:187], v[0:3]
	v_mfma_f32_16x16x32_bf16 v[56:59], v[148:151], v[164:167], v[56:59]
	v_mfma_f32_16x16x32_bf16 v[48:51], v[156:159], v[164:167], v[48:51]
	v_mfma_f32_16x16x32_bf16 v[40:43], v[148:151], v[172:175], v[40:43]
	v_mfma_f32_16x16x32_bf16 v[32:35], v[156:159], v[172:175], v[32:35]
	v_mfma_f32_16x16x32_bf16 v[24:27], v[148:151], v[180:183], v[24:27]
	v_mfma_f32_16x16x32_bf16 v[16:19], v[156:159], v[180:183], v[16:19]
	v_mfma_f32_16x16x32_bf16 v[8:11], v[148:151], v[188:191], v[8:11]
	v_mfma_f32_16x16x32_bf16 v[0:3], v[156:159], v[188:191], v[0:3]
	s_barrier
	s_add_i32 s59, s59, 2
	s_add_u32 s57, s57, 0x100
	s_addc_u32 s58, s58, 0
	s_cmp_gt_u32 s59, 41
	s_mov_b64 s[10:11], s[8:9]
	s_cbranch_scc0 .LBB0_1024
	s_and_b64 vcc, exec, s[66:67]
	s_cbranch_vccz .LBB0_1027
	s_barrier
; __device__ __forceinline__ unsigned cvtpk(float lo, float hi) { f32x2 v = {lo, hi}; bf16x2_t b = __builtin_convertvector(v, bf16x2_t); return __builtin_bit_cast(unsigned, b); }
;     __device__ __forceinline__ void operator()(const pg8::f32x4 (&acc)[2][2][4][2], const pg8::Unit& u, int wr, int wc, int fr, int fq) const {
;         const int kind = p->kind, ldc = p->ldc, ncols = p->ncols, flags = p->flags; const float coef = p->coef;
;         const float* fin = (const float*)p->fin; float* fout = (float*)p->fout; bf16_t* o0 = (bf16_t*)p->o0; bf16_t* o1 = (bf16_t*)p->o1; const float* aux = (const float*)p->aux;
;         const int rowb = u.pm * 256 + wr * 64 + fr;
;         const int colb = u.pn * 256 + wc * 32 + (PERM ? 8 : 4) * fq;
;         constexpr int NS = PERM ? 4 : 16;
;         if (kind == EK_ACT) {
;             float rsv[2][4];
; #pragma unroll
;             for (int ai = 0; ai < 2; ++ai)
; #pragma unroll
;                 for (int m = 0; m < 4; ++m) rsv[ai][m] = fin[rowb + 128 * ai + 16 * m];
;     ...
;         } else if (kind == EK_BF16 && PERM) {
; #pragma unroll
;             for (int bj = 0; bj < 2; ++bj) {
;                 const int c = colb + 128 * bj;
;                 if (c < ncols) {
; #pragma unroll
;                     for (int ai = 0; ai < 2; ++ai)
; #pragma unroll
;                         for (int m = 0; m < 4; ++m) {
;                             pg8::f32x4 v0 = acc[ai][bj][m][0], v1 = acc[ai][bj][m][1];
;                             if (flags & 4) { const float rs = __builtin_amdgcn_rsqf(fin[rowb + 128 * ai + 16 * m] * (1.0f / DM) + EPS); v0 = v0 * rs; v1 = v1 * rs; }
;                             *(u32x4*)(o0 + (size_t)(rowb + 128 * ai + 16 * m) * ldc + c) = (u32x4){cvtpk(v0[0], v0[1]), cvtpk(v0[2], v0[3]), cvtpk(v1[0], v1[1]), cvtpk(v1[2], v1[3])};
;                         }
.LBB0_1027:
	s_setprio 0
	v_mov_b32_e32 v64, v192
	v_mov_b32_e32 v65, v193
	v_mov_b32_e32 v66, v194
	v_mov_b32_e32 v67, v195
	v_mov_b32_e32 v68, v196
	v_mov_b32_e32 v69, v197
	v_mov_b32_e32 v70, v198
	v_mov_b32_e32 v71, v199
	v_mov_b32_e32 v136, v200
	v_mov_b32_e32 v137, v201
	v_mov_b32_e32 v138, v202
	v_mov_b32_e32 v139, v203
	v_lshl_add_u32 v228, s56, 8, v252
	s_mov_b64 s[8:9], -1
	v_readfirstlane_b32 s50, v192
	s_cmp_lt_i32 s50, 1
	s_cbranch_scc1 .LBB0_1119
	v_lshl_or_b32 v230, s55, 8, v248
	s_cmp_lt_i32 s50, 2
	s_cbranch_scc1 .LBB0_1068
	s_cmp_eq_u32 s50, 2
	s_cbranch_scc0 .LBB0_1067
	v_and_b32_e32 v64, 4, v67
	v_cmp_ne_u32_e64 s[8:9], 0, v64
	v_cmp_lt_i32_e32 vcc, v230, v66
	s_nop 0
	v_cndmask_b32_e64 v64, 0, 1, s[8:9]
	v_cmp_ne_u32_e64 s[8:9], 1, v64
	s_and_saveexec_b64 s[10:11], vcc
	s_cbranch_execz .LBB0_1048
	v_ashrrev_i32_e32 v229, 31, v228
	v_mov_b64_e32 v[142:143], v[134:135]
	v_mov_b64_e32 v[146:147], v[130:131]
	s_and_b64 vcc, exec, s[8:9]
	v_lshl_add_u64 v[150:151], v[228:229], 2, v[136:137]
	v_mov_b64_e32 v[140:141], v[132:133]
	v_mov_b64_e32 v[144:145], v[128:129]
	s_cbranch_vccnz .LBB0_1033
	global_load_dword v64, v[150:151], off
	s_waitcnt vmcnt(0)
	v_fmamk_f32 v64, v64, 0x3a800000, v244
	v_rsq_f32_e32 v64, v64
	s_nop 0
	v_pk_mul_f32 v[142:143], v[134:135], v[64:65] op_sel_hi:[1,0]
	v_pk_mul_f32 v[140:141], v[132:133], v[64:65] op_sel_hi:[1,0]
	v_pk_mul_f32 v[146:147], v[130:131], v[64:65] op_sel_hi:[1,0]
	v_pk_mul_f32 v[144:145], v[128:129], v[64:65] op_sel_hi:[1,0]

; #define PG8_STAGE(bufoff, gbase, voff) do { _Pragma("unroll") for (int _i = 0; _i < 2; ++_i) \
;         __builtin_amdgcn_global_load_lds((const unsigned*)((const char*)(gbase) + (voff)[_i]), (PG8_LAS unsigned*)(lds + (bufoff) + ldsw + _i * 8192), 16, 0, 0); } while (0)
; #define PG8_LDA(dst, b, h) do { _Pragma("unroll") for (int m = 0; m < 4; ++m) _Pragma("unroll") for (int k = 0; k < 2; ++k) dst[m][k] = *(const PG8_LAS bf16x8*)(lds + PG8_SA(b, h) + aoff + m * 2048 + k * 1024); } while (0)
; #define PG8_LDB(dst, b, h) do { _Pragma("unroll") for (int n = 0; n < 2; ++n) _Pragma("unroll") for (int k = 0; k < 2; ++k) dst[n][k] = *(const PG8_LAS bf16x8*)(lds + PG8_SB(b, h) + boff + n * 2048 + k * 1024); } while (0)
; #define PG8_WAIT_V(n) asm volatile("s_waitcnt vmcnt(" #n ")" ::: "memory")
; #define PG8_WAIT_L(n) asm volatile("s_waitcnt lgkmcnt(" #n ")" ::: "memory")
; #define PG8_BAR __builtin_amdgcn_s_barrier()
; #define PG8_SCHED __builtin_amdgcn_sched_barrier(0)
; template <class Epi, class Sched, bool ALIGN_EPI = false, bool SP2 = false>
; __device__ __forceinline__ void gemm_phase(PG8_LAS unsigned char* lds, const Gemm g, const Sched& S, const Epi& E, const int wave0) {
;     ...
;     for (;;) {
;         const bool has_next = S.next(ui + 1, nxt);
;         const char* nA = has_next ? (const char*)g.A + (size_t)nxt.pm * tstep : cA; const char* nB = has_next ? (const char*)g.Bt + (size_t)nxt.pn * tstep : cB;
;         for (int t = 0; t < nt; t += 2) {
;             const bool last = (t == nt - 2);
;             const char* a1 = cA + (size_t)(t + 1) * kstep;
;             const char* a2 = last ? nA : cA + (size_t)(t + 2) * kstep; const char* b2 = last ? nB : cB + (size_t)(t + 2) * kstep;
;             const char* a3 = a2 + kstep; const char* b3 = b2 + kstep;
;             if (last && has_next) S.a_ready(nxt);
;             if constexpr (SP2) {
;             PG8_LDB(B0, 0, 0); PG8_LDB(B1, 0, 1); PG8_SCHED; PG8_LDA(At, 0, 0); PG8_STAGE(PG8_SA(1, 1), a1 + hstep, voffA);
;             PG8_WAIT_V(8); PG8_WAIT_L(0); PG8_BAR; PG8_MMA(0, 0, At, B0); PG8_MMA(0, 1, At, B1); PG8_BAR; PG8_SCHED;
;             PG8_LDA(At, 0, 1); PG8_STAGE(PG8_SB(0, 0), b2, voffB); PG8_STAGE(PG8_SB(0, 1), b2 + hstep, voffB); PG8_STAGE(PG8_SA(0, 0), a2, voffA);
;             PG8_WAIT_V(8); PG8_WAIT_L(0); PG8_BAR; PG8_MMA(1, 0, At, B0); PG8_MMA(1, 1, At, B1); PG8_BAR; PG8_SCHED;
.Lsp_skip_1140:
	s_ashr_i32 s49, s48, 31
	s_lshl_b64 s[18:19], s[48:49], 19
	s_add_u32 s50, s36, s18
	s_addc_u32 s51, s37, s19
	s_and_b64 s[18:19], s[6:7], exec
	s_cselect_b32 s9, s51, s11
	s_cselect_b32 s49, s50, s10
	s_ashr_i32 s47, s46, 31
	s_lshl_b64 s[18:19], s[46:47], 19
	s_add_u32 s52, s38, s18
	s_addc_u32 s53, s39, s19
	s_and_b64 s[18:19], s[6:7], exec
	s_cselect_b32 s47, s53, s57
	s_cselect_b32 s60, s52, s56
	s_add_u32 s10, s10, 0x40080
	s_addc_u32 s11, s11, 0
	s_add_u32 s61, s56, 0x100
	s_addc_u32 s62, s57, 0
	s_mov_b32 s63, -2
	global_load_dwordx4 v[192:195], v215, s[40:41] offset:1024
	global_load_dwordx4 v[196:199], v215, s[40:41] offset:1064
	global_load_dwordx4 v[200:203], v215, s[40:41] offset:1048
	s_waitcnt lgkmcnt(0)
	s_add_u32 s18, s10, 0xfffc0080
	s_addc_u32 s19, s11, -1
	s_add_i32 s64, 0, 0x10000
	s_cmp_eq_u32 s63, 12
	s_cselect_b32 s59, s9, s19
	s_cselect_b32 s58, s49, s18
	s_cselect_b32 s57, s47, s62
	s_cselect_b32 s56, s60, s61
	s_add_i32 s65, 0, 0x14000
	v_add_u32_e32 v140, s64, v247
	v_add_u32_e32 v156, s65, v247
	ds_read_b128 v[64:67], v140
	ds_read_b128 v[68:71], v140 offset:1024
	ds_read_b128 v[136:139], v140 offset:2048
	ds_read_b128 v[140:143], v140 offset:3072
	ds_read_b128 v[144:147], v156
	ds_read_b128 v[148:151], v156 offset:1024
	ds_read_b128 v[152:155], v156 offset:2048
	ds_read_b128 v[156:159], v156 offset:3072
	s_add_i32 m0, s33, 0xc000
	ds_read_b128 v[160:163], v245
	ds_read_b128 v[164:167], v245 offset:1024
	ds_read_b128 v[168:171], v245 offset:2048
	ds_read_b128 v[172:175], v245 offset:3072
	ds_read_b128 v[176:179], v245 offset:4096
	ds_read_b128 v[180:183], v245 offset:5120
	ds_read_b128 v[184:187], v245 offset:6144
	ds_read_b128 v[188:191], v245 offset:7168
	global_load_lds_dwordx4 v224, s[10:11]
	s_add_i32 m0, s33, 0xe000
	s_nop 0
	global_load_lds_dwordx4 v226, s[10:11]
	s_waitcnt vmcnt(8)
	s_waitcnt lgkmcnt(0)
	s_barrier
	v_mfma_f32_16x16x32_bf16 v[132:135], v[64:67], v[160:163], 0
	v_mfma_f32_16x16x32_bf16 v[128:131], v[136:139], v[160:163], 0
	v_mfma_f32_16x16x32_bf16 v[116:119], v[64:67], v[168:171], 0
	v_mfma_f32_16x16x32_bf16 v[108:111], v[136:139], v[168:171], 0
	v_mfma_f32_16x16x32_bf16 v[100:103], v[64:67], v[176:179], 0
	v_mfma_f32_16x16x32_bf16 v[92:95], v[136:139], v[176:179], 0
	v_mfma_f32_16x16x32_bf16 v[84:87], v[64:67], v[184:187], 0
	v_mfma_f32_16x16x32_bf16 v[76:79], v[136:139], v[184:187], 0
	v_mfma_f32_16x16x32_bf16 v[132:135], v[68:71], v[164:167], v[132:135]
	v_mfma_f32_16x16x32_bf16 v[128:131], v[140:143], v[164:167], v[128:131]
	v_mfma_f32_16x16x32_bf16 v[116:119], v[68:71], v[172:175], v[116:119]
	v_mfma_f32_16x16x32_bf16 v[108:111], v[140:143], v[172:175], v[108:111]
	v_mfma_f32_16x16x32_bf16 v[100:103], v[68:71], v[180:183], v[100:103]
	v_mfma_f32_16x16x32_bf16 v[92:95], v[140:143], v[180:183], v[92:95]
	v_mfma_f32_16x16x32_bf16 v[84:87], v[68:71], v[188:191], v[84:87]
	v_mfma_f32_16x16x32_bf16 v[76:79], v[140:143], v[188:191], v[76:79]
	v_mfma_f32_16x16x32_bf16 v[124:127], v[144:147], v[160:163], 0
	v_mfma_f32_16x16x32_bf16 v[120:123], v[152:155], v[160:163], 0
	v_mfma_f32_16x16x32_bf16 v[112:115], v[144:147], v[168:171], 0
	v_mfma_f32_16x16x32_bf16 v[104:107], v[152:155], v[168:171], 0
	v_mfma_f32_16x16x32_bf16 v[96:99], v[144:147], v[176:179], 0
	v_mfma_f32_16x16x32_bf16 v[88:91], v[152:155], v[176:179], 0
	v_mfma_f32_16x16x32_bf16 v[80:83], v[144:147], v[184:187], 0
	v_mfma_f32_16x16x32_bf16 v[72:75], v[152:155], v[184:187], 0
	v_mfma_f32_16x16x32_bf16 v[124:127], v[148:151], v[164:167], v[124:127]
	v_mfma_f32_16x16x32_bf16 v[120:123], v[156:159], v[164:167], v[120:123]
	v_mfma_f32_16x16x32_bf16 v[112:115], v[148:151], v[172:175], v[112:115]
	v_mfma_f32_16x16x32_bf16 v[104:107], v[156:159], v[172:175], v[104:107]
	v_mfma_f32_16x16x32_bf16 v[96:99], v[148:151], v[180:183], v[96:99]
	v_mfma_f32_16x16x32_bf16 v[88:91], v[156:159], v[180:183], v[88:91]
	v_mfma_f32_16x16x32_bf16 v[80:83], v[148:151], v[188:191], v[80:83]
	v_mfma_f32_16x16x32_bf16 v[72:75], v[156:159], v[188:191], v[72:75]
	s_barrier
	s_add_i32 s18, s64, s95
	s_mov_b32 m0, s18
	ds_read_b128 v[160:163], v245 offset:16384
	ds_read_b128 v[164:167], v245 offset:17408
	ds_read_b128 v[168:171], v245 offset:18432
	ds_read_b128 v[172:175], v245 offset:19456
	ds_read_b128 v[176:179], v245 offset:20480
	ds_read_b128 v[180:183], v245 offset:21504
	ds_read_b128 v[184:187], v245 offset:22528
	ds_read_b128 v[188:191], v245 offset:23552
	global_load_lds_dwordx4 v218, s[56:57]
	s_add_i32 m0, s18, 0x2000
	s_add_u32 s18, s56, 0x40000
	s_addc_u32 s19, s57, 0
	s_add_i32 s64, s65, s95
	global_load_lds_dwordx4 v222, s[56:57]
	s_mov_b32 m0, s64
	s_nop 0
	global_load_lds_dwordx4 v218, s[18:19]
	s_add_i32 m0, s64, 0x2000
	s_nop 0
	global_load_lds_dwordx4 v222, s[18:19]
	s_mov_b32 m0, s33
	s_nop 0
	global_load_lds_dwordx4 v216, s[58:59]
	s_mov_b32 m0, s82
	s_nop 0
	global_load_lds_dwordx4 v220, s[58:59]
	s_waitcnt vmcnt(8)
	s_waitcnt lgkmcnt(0)
	s_barrier
; #define PG8_STAGE(bufoff, gbase, voff) do { _Pragma("unroll") for (int _i = 0; _i < 2; ++_i) \
;         __builtin_amdgcn_global_load_lds((const unsigned*)((const char*)(gbase) + (voff)[_i]), (PG8_LAS unsigned*)(lds + (bufoff) + ldsw + _i * 8192), 16, 0, 0); } while (0)
; #define PG8_LDA(dst, b, h) do { _Pragma("unroll") for (int m = 0; m < 4; ++m) _Pragma("unroll") for (int k = 0; k < 2; ++k) dst[m][k] = *(const PG8_LAS bf16x8*)(lds + PG8_SA(b, h) + aoff + m * 2048 + k * 1024); } while (0)
; #define PG8_LDB(dst, b, h) do { _Pragma("unroll") for (int n = 0; n < 2; ++n) _Pragma("unroll") for (int k = 0; k < 2; ++k) dst[n][k] = *(const PG8_LAS bf16x8*)(lds + PG8_SB(b, h) + boff + n * 2048 + k * 1024); } while (0)
; #define PG8_MMA(ai, bj, At, Bt) do { __builtin_amdgcn_s_setprio(1); _Pragma("unroll") for (int m = 0; m < 4; ++m) _Pragma("unroll") for (int n = 0; n < 2; ++n) _Pragma("unroll") for (int k = 0; k < 2; ++k) \
;         acc[ai][bj][m][n] = __builtin_amdgcn_mfma_f32_16x16x32_bf16(Bt[n][k], At[m][k], acc[ai][bj][m][n], 0, 0, 0); __builtin_amdgcn_s_setprio(0); } while (0)
; #define PG8_WAIT_V(n) asm volatile("s_waitcnt vmcnt(" #n ")" ::: "memory")
; #define PG8_WAIT_L(n) asm volatile("s_waitcnt lgkmcnt(" #n ")" ::: "memory")
; #define PG8_BAR __builtin_amdgcn_s_barrier()
; #define PG8_SCHED __builtin_amdgcn_sched_barrier(0)
; template <class Epi, class Sched, bool ALIGN_EPI = false, bool SP2 = false>
; __device__ __forceinline__ void gemm_phase(PG8_LAS unsigned char* lds, const Gemm g, const Sched& S, const Epi& E, const int wave0) {
;     ...
;             PG8_WAIT_V(8); PG8_WAIT_L(0); PG8_BAR; PG8_MMA(1, 0, At, B0); PG8_MMA(1, 1, At, B1); PG8_BAR; PG8_SCHED;
;             PG8_LDB(B0, 1, 0); PG8_LDB(B1, 1, 1); PG8_SCHED; PG8_LDA(At, 1, 0); PG8_STAGE(PG8_SA(0, 1), a2 + hstep, voffA);
;             PG8_WAIT_V(8); PG8_WAIT_L(0); PG8_BAR; PG8_MMA(0, 0, At, B0); PG8_MMA(0, 1, At, B1); PG8_BAR; PG8_SCHED;
	v_mfma_f32_16x16x32_bf16 v[60:63], v[64:67], v[160:163], 0
	v_mfma_f32_16x16x32_bf16 v[52:55], v[136:139], v[160:163], 0
	v_mfma_f32_16x16x32_bf16 v[44:47], v[64:67], v[168:171], 0
	v_mfma_f32_16x16x32_bf16 v[36:39], v[136:139], v[168:171], 0
	v_mfma_f32_16x16x32_bf16 v[28:31], v[64:67], v[176:179], 0
	v_mfma_f32_16x16x32_bf16 v[20:23], v[136:139], v[176:179], 0
	v_mfma_f32_16x16x32_bf16 v[12:15], v[64:67], v[184:187], 0
	v_mfma_f32_16x16x32_bf16 v[4:7], v[136:139], v[184:187], 0
	v_mfma_f32_16x16x32_bf16 v[60:63], v[68:71], v[164:167], v[60:63]
	v_mfma_f32_16x16x32_bf16 v[52:55], v[140:143], v[164:167], v[52:55]
	v_mfma_f32_16x16x32_bf16 v[44:47], v[68:71], v[172:175], v[44:47]
	v_mfma_f32_16x16x32_bf16 v[36:39], v[140:143], v[172:175], v[36:39]
	v_mfma_f32_16x16x32_bf16 v[28:31], v[68:71], v[180:183], v[28:31]
	v_mfma_f32_16x16x32_bf16 v[20:23], v[140:143], v[180:183], v[20:23]
	v_mfma_f32_16x16x32_bf16 v[12:15], v[68:71], v[188:191], v[12:15]
	v_mfma_f32_16x16x32_bf16 v[4:7], v[140:143], v[188:191], v[4:7]
	v_mfma_f32_16x16x32_bf16 v[56:59], v[144:147], v[160:163], 0
	v_mfma_f32_16x16x32_bf16 v[48:51], v[152:155], v[160:163], 0
	v_mfma_f32_16x16x32_bf16 v[40:43], v[144:147], v[168:171], 0
	v_mfma_f32_16x16x32_bf16 v[32:35], v[152:155], v[168:171], 0
	v_mfma_f32_16x16x32_bf16 v[24:27], v[144:147], v[176:179], 0
	v_mfma_f32_16x16x32_bf16 v[16:19], v[152:155], v[176:179], 0
	v_mfma_f32_16x16x32_bf16 v[8:11], v[144:147], v[184:187], 0
	v_mfma_f32_16x16x32_bf16 v[0:3], v[152:155], v[184:187], 0
	v_mfma_f32_16x16x32_bf16 v[56:59], v[148:151], v[164:167], v[56:59]
	v_mfma_f32_16x16x32_bf16 v[48:51], v[156:159], v[164:167], v[48:51]
	v_mfma_f32_16x16x32_bf16 v[40:43], v[148:151], v[172:175], v[40:43]
	v_mfma_f32_16x16x32_bf16 v[32:35], v[156:159], v[172:175], v[32:35]
	v_mfma_f32_16x16x32_bf16 v[24:27], v[148:151], v[180:183], v[24:27]
	v_mfma_f32_16x16x32_bf16 v[16:19], v[156:159], v[180:183], v[16:19]
	v_mfma_f32_16x16x32_bf16 v[8:11], v[148:151], v[188:191], v[8:11]
	v_mfma_f32_16x16x32_bf16 v[0:3], v[156:159], v[188:191], v[0:3]
	s_barrier
	s_add_i32 s64, 0, 0x18000
	s_add_i32 s65, 0, 0x1c000
	v_add_u32_e32 v140, s64, v247
	v_add_u32_e32 v156, s65, v247
	ds_read_b128 v[64:67], v140
	ds_read_b128 v[68:71], v140 offset:1024
	ds_read_b128 v[136:139], v140 offset:2048
	ds_read_b128 v[140:143], v140 offset:3072
	ds_read_b128 v[144:147], v156
	ds_read_b128 v[148:151], v156 offset:1024
	ds_read_b128 v[152:155], v156 offset:2048
	ds_read_b128 v[156:159], v156 offset:3072
	s_add_u32 s18, s58, 0x40000
	s_addc_u32 s19, s59, 0
	s_mov_b32 m0, s16
	ds_read_b128 v[160:163], v245 offset:32768
	ds_read_b128 v[164:167], v245 offset:33792
	ds_read_b128 v[168:171], v245 offset:34816
	ds_read_b128 v[172:175], v245 offset:35840
	ds_read_b128 v[176:179], v245 offset:36864
	ds_read_b128 v[180:183], v245 offset:37888
	ds_read_b128 v[184:187], v245 offset:38912
	ds_read_b128 v[188:191], v245 offset:39936
	global_load_lds_dwordx4 v216, s[18:19]
	s_mov_b32 m0, s83
	s_nop 0
	global_load_lds_dwordx4 v220, s[18:19]
	s_waitcnt vmcnt(8)
	s_waitcnt lgkmcnt(0)
	s_barrier
	v_mfma_f32_16x16x32_bf16 v[132:135], v[64:67], v[160:163], v[132:135]
	v_mfma_f32_16x16x32_bf16 v[128:131], v[136:139], v[160:163], v[128:131]
	v_mfma_f32_16x16x32_bf16 v[116:119], v[64:67], v[168:171], v[116:119]
	v_mfma_f32_16x16x32_bf16 v[108:111], v[136:139], v[168:171], v[108:111]
	v_mfma_f32_16x16x32_bf16 v[100:103], v[64:67], v[176:179], v[100:103]
	v_mfma_f32_16x16x32_bf16 v[92:95], v[136:139], v[176:179], v[92:95]
	v_mfma_f32_16x16x32_bf16 v[84:87], v[64:67], v[184:187], v[84:87]
	v_mfma_f32_16x16x32_bf16 v[76:79], v[136:139], v[184:187], v[76:79]
	v_mfma_f32_16x16x32_bf16 v[132:135], v[68:71], v[164:167], v[132:135]
	v_mfma_f32_16x16x32_bf16 v[128:131], v[140:143], v[164:167], v[128:131]
	v_mfma_f32_16x16x32_bf16 v[116:119], v[68:71], v[172:175], v[116:119]
	v_mfma_f32_16x16x32_bf16 v[108:111], v[140:143], v[172:175], v[108:111]
	v_mfma_f32_16x16x32_bf16 v[100:103], v[68:71], v[180:183], v[100:103]
	v_mfma_f32_16x16x32_bf16 v[92:95], v[140:143], v[180:183], v[92:95]
	v_mfma_f32_16x16x32_bf16 v[84:87], v[68:71], v[188:191], v[84:87]
	v_mfma_f32_16x16x32_bf16 v[76:79], v[140:143], v[188:191], v[76:79]
	v_mfma_f32_16x16x32_bf16 v[124:127], v[144:147], v[160:163], v[124:127]
	v_mfma_f32_16x16x32_bf16 v[120:123], v[152:155], v[160:163], v[120:123]
	v_mfma_f32_16x16x32_bf16 v[112:115], v[144:147], v[168:171], v[112:115]
	v_mfma_f32_16x16x32_bf16 v[104:107], v[152:155], v[168:171], v[104:107]
	v_mfma_f32_16x16x32_bf16 v[96:99], v[144:147], v[176:179], v[96:99]
	v_mfma_f32_16x16x32_bf16 v[88:91], v[152:155], v[176:179], v[88:91]
	v_mfma_f32_16x16x32_bf16 v[80:83], v[144:147], v[184:187], v[80:83]
	v_mfma_f32_16x16x32_bf16 v[72:75], v[152:155], v[184:187], v[72:75]
	v_mfma_f32_16x16x32_bf16 v[124:127], v[148:151], v[164:167], v[124:127]
	v_mfma_f32_16x16x32_bf16 v[120:123], v[156:159], v[164:167], v[120:123]
	v_mfma_f32_16x16x32_bf16 v[112:115], v[148:151], v[172:175], v[112:115]
	v_mfma_f32_16x16x32_bf16 v[104:107], v[156:159], v[172:175], v[104:107]
	v_mfma_f32_16x16x32_bf16 v[96:99], v[148:151], v[180:183], v[96:99]
	v_mfma_f32_16x16x32_bf16 v[88:91], v[156:159], v[180:183], v[88:91]
	v_mfma_f32_16x16x32_bf16 v[80:83], v[148:151], v[188:191], v[80:83]
	v_mfma_f32_16x16x32_bf16 v[72:75], v[156:159], v[188:191], v[72:75]
	s_barrier
; #define PG8_STAGE(bufoff, gbase, voff) do { _Pragma("unroll") for (int _i = 0; _i < 2; ++_i) \
;         __builtin_amdgcn_global_load_lds((const unsigned*)((const char*)(gbase) + (voff)[_i]), (PG8_LAS unsigned*)(lds + (bufoff) + ldsw + _i * 8192), 16, 0, 0); } while (0)
; #define PG8_LDA(dst, b, h) do { _Pragma("unroll") for (int m = 0; m < 4; ++m) _Pragma("unroll") for (int k = 0; k < 2; ++k) dst[m][k] = *(const PG8_LAS bf16x8*)(lds + PG8_SA(b, h) + aoff + m * 2048 + k * 1024); } while (0)
; #define PG8_LDB(dst, b, h) do { _Pragma("unroll") for (int n = 0; n < 2; ++n) _Pragma("unroll") for (int k = 0; k < 2; ++k) dst[n][k] = *(const PG8_LAS bf16x8*)(lds + PG8_SB(b, h) + boff + n * 2048 + k * 1024); } while (0)
; #define PG8_MMA(ai, bj, At, Bt) do { __builtin_amdgcn_s_setprio(1); _Pragma("unroll") for (int m = 0; m < 4; ++m) _Pragma("unroll") for (int n = 0; n < 2; ++n) _Pragma("unroll") for (int k = 0; k < 2; ++k) \
;         acc[ai][bj][m][n] = __builtin_amdgcn_mfma_f32_16x16x32_bf16(Bt[n][k], At[m][k], acc[ai][bj][m][n], 0, 0, 0); __builtin_amdgcn_s_setprio(0); } while (0)
; #define PG8_BAR __builtin_amdgcn_s_barrier()
; template <class Epi, class Sched, bool ALIGN_EPI = false, bool SP2 = false>
; __device__ __forceinline__ void gemm_phase(PG8_LAS unsigned char* lds, const Gemm g, const Sched& S, const Epi& E, const int wave0) {
;     ...
;             PG8_LDB(B0, 0, 0); PG8_LDB(B1, 0, 1); PG8_SCHED; PG8_LDA(At, 0, 0); PG8_STAGE(PG8_SA(1, 1), a1 + hstep, voffA);
;             PG8_WAIT_V(8); PG8_WAIT_L(0); PG8_BAR; PG8_MMA(0, 0, At, B0); PG8_MMA(0, 1, At, B1); PG8_BAR; PG8_SCHED;
;             PG8_LDA(At, 0, 1); PG8_STAGE(PG8_SB(0, 0), b2, voffB); PG8_STAGE(PG8_SB(0, 1), b2 + hstep, voffB); PG8_STAGE(PG8_SA(0, 0), a2, voffA);
;             PG8_WAIT_V(8); PG8_WAIT_L(0); PG8_BAR; PG8_MMA(1, 0, At, B0); PG8_MMA(1, 1, At, B1); PG8_BAR; PG8_SCHED;
;             PG8_LDB(B0, 1, 0); PG8_LDB(B1, 1, 1); PG8_SCHED; PG8_LDA(At, 1, 0); PG8_STAGE(PG8_SA(0, 1), a2 + hstep, voffA);
;             PG8_WAIT_V(8); PG8_WAIT_L(0); PG8_BAR; PG8_MMA(0, 0, At, B0); PG8_MMA(0, 1, At, B1); PG8_BAR; PG8_SCHED;
;             PG8_LDA(At, 1, 1); PG8_STAGE(PG8_SB(1, 0), b3, voffB); PG8_STAGE(PG8_SB(1, 1), b3 + hstep, voffB); PG8_STAGE(PG8_SA(1, 0), a3, voffA);
;             PG8_WAIT_V(8); PG8_WAIT_L(0); PG8_BAR; PG8_MMA(1, 0, At, B0); PG8_MMA(1, 1, At, B1); PG8_BAR; PG8_SCHED;
	s_add_i32 s18, s64, s95
	s_add_i32 m0, s18, 0xffffff80
	ds_read_b128 v[160:163], v245 offset:49152
	ds_read_b128 v[164:167], v245 offset:50176
	ds_read_b128 v[168:171], v245 offset:51200
	ds_read_b128 v[172:175], v245 offset:52224
	ds_read_b128 v[176:179], v245 offset:53248
	ds_read_b128 v[180:183], v245 offset:54272
	ds_read_b128 v[184:187], v245 offset:55296
	ds_read_b128 v[188:191], v245 offset:56320
	global_load_lds_dwordx4 v218, s[56:57] offset:128
	s_add_i32 m0, s18, 0x1f80
	s_add_u32 s18, s56, 0x40080
	s_addc_u32 s19, s57, 0
	global_load_lds_dwordx4 v222, s[56:57] offset:128
	s_add_i32 s56, s65, s95
	s_mov_b32 m0, s56
	s_nop 0
	global_load_lds_dwordx4 v218, s[18:19]
	s_add_i32 m0, s56, 0x2000
	s_nop 0
	global_load_lds_dwordx4 v222, s[18:19]
	s_add_i32 m0, s17, 0xffffff80
	s_nop 0
	global_load_lds_dwordx4 v216, s[58:59] offset:128
	s_add_i32 m0, s23, 0xffffff80
	s_nop 0
	global_load_lds_dwordx4 v220, s[58:59] offset:128
	s_waitcnt vmcnt(8)
	s_waitcnt lgkmcnt(0)
	s_barrier
	v_mfma_f32_16x16x32_bf16 v[60:63], v[64:67], v[160:163], v[60:63]
	v_mfma_f32_16x16x32_bf16 v[52:55], v[136:139], v[160:163], v[52:55]
	v_mfma_f32_16x16x32_bf16 v[44:47], v[64:67], v[168:171], v[44:47]
	v_mfma_f32_16x16x32_bf16 v[36:39], v[136:139], v[168:171], v[36:39]
	v_mfma_f32_16x16x32_bf16 v[28:31], v[64:67], v[176:179], v[28:31]
	v_mfma_f32_16x16x32_bf16 v[20:23], v[136:139], v[176:179], v[20:23]
	v_mfma_f32_16x16x32_bf16 v[12:15], v[64:67], v[184:187], v[12:15]
	v_mfma_f32_16x16x32_bf16 v[4:7], v[136:139], v[184:187], v[4:7]
	v_mfma_f32_16x16x32_bf16 v[60:63], v[68:71], v[164:167], v[60:63]
	v_mfma_f32_16x16x32_bf16 v[52:55], v[140:143], v[164:167], v[52:55]
	v_mfma_f32_16x16x32_bf16 v[44:47], v[68:71], v[172:175], v[44:47]
	v_mfma_f32_16x16x32_bf16 v[36:39], v[140:143], v[172:175], v[36:39]
	v_mfma_f32_16x16x32_bf16 v[28:31], v[68:71], v[180:183], v[28:31]
	v_mfma_f32_16x16x32_bf16 v[20:23], v[140:143], v[180:183], v[20:23]
	v_mfma_f32_16x16x32_bf16 v[12:15], v[68:71], v[188:191], v[12:15]
	v_mfma_f32_16x16x32_bf16 v[4:7], v[140:143], v[188:191], v[4:7]
	v_mfma_f32_16x16x32_bf16 v[56:59], v[144:147], v[160:163], v[56:59]
	v_mfma_f32_16x16x32_bf16 v[48:51], v[152:155], v[160:163], v[48:51]
	v_mfma_f32_16x16x32_bf16 v[40:43], v[144:147], v[168:171], v[40:43]
	v_mfma_f32_16x16x32_bf16 v[32:35], v[152:155], v[168:171], v[32:35]
	v_mfma_f32_16x16x32_bf16 v[24:27], v[144:147], v[176:179], v[24:27]
	v_mfma_f32_16x16x32_bf16 v[16:19], v[152:155], v[176:179], v[16:19]
	v_mfma_f32_16x16x32_bf16 v[8:11], v[144:147], v[184:187], v[8:11]
	v_mfma_f32_16x16x32_bf16 v[0:3], v[152:155], v[184:187], v[0:3]
	v_mfma_f32_16x16x32_bf16 v[56:59], v[148:151], v[164:167], v[56:59]
	v_mfma_f32_16x16x32_bf16 v[48:51], v[156:159], v[164:167], v[48:51]
	v_mfma_f32_16x16x32_bf16 v[40:43], v[148:151], v[172:175], v[40:43]
	v_mfma_f32_16x16x32_bf16 v[32:35], v[156:159], v[172:175], v[32:35]
	v_mfma_f32_16x16x32_bf16 v[24:27], v[148:151], v[180:183], v[24:27]
	v_mfma_f32_16x16x32_bf16 v[16:19], v[156:159], v[180:183], v[16:19]
	v_mfma_f32_16x16x32_bf16 v[8:11], v[148:151], v[188:191], v[8:11]
	v_mfma_f32_16x16x32_bf16 v[0:3], v[156:159], v[188:191], v[0:3]
	s_barrier
	s_add_i32 s63, s63, 2
	s_add_u32 s10, s10, 0x100
	s_addc_u32 s11, s11, 0
	s_add_u32 s61, s61, 0x100
	s_addc_u32 s62, s62, 0
	s_cmp_gt_u32 s63, 13
.LBB0_1140:
	s_add_u32 s18, s10, 0xfffc0080
	s_addc_u32 s19, s11, -1
	s_add_i32 s64, 0, 0x10000
	s_cmp_eq_u32 s63, 12
	s_cselect_b32 s59, s9, s19
	s_cselect_b32 s58, s49, s18
	s_cselect_b32 s57, s47, s62
	s_cselect_b32 s56, s60, s61
	s_add_i32 s65, 0, 0x14000
	v_add_u32_e32 v140, s64, v247
	v_add_u32_e32 v156, s65, v247
	ds_read_b128 v[64:67], v140
	ds_read_b128 v[68:71], v140 offset:1024
	ds_read_b128 v[136:139], v140 offset:2048
	ds_read_b128 v[140:143], v140 offset:3072
	ds_read_b128 v[144:147], v156
	ds_read_b128 v[148:151], v156 offset:1024
	ds_read_b128 v[152:155], v156 offset:2048
	ds_read_b128 v[156:159], v156 offset:3072
	s_add_i32 m0, s33, 0xc000
	ds_read_b128 v[160:163], v245
	ds_read_b128 v[164:167], v245 offset:1024
	ds_read_b128 v[168:171], v245 offset:2048
	ds_read_b128 v[172:175], v245 offset:3072
	ds_read_b128 v[176:179], v245 offset:4096
	ds_read_b128 v[180:183], v245 offset:5120
	ds_read_b128 v[184:187], v245 offset:6144
	ds_read_b128 v[188:191], v245 offset:7168
	global_load_lds_dwordx4 v224, s[10:11]
	s_add_i32 m0, s33, 0xe000
	s_nop 0
	global_load_lds_dwordx4 v226, s[10:11]
	s_waitcnt vmcnt(8)
	s_waitcnt lgkmcnt(0)
	s_barrier
	v_mfma_f32_16x16x32_bf16 v[132:135], v[64:67], v[160:163], v[132:135]
	v_mfma_f32_16x16x32_bf16 v[128:131], v[136:139], v[160:163], v[128:131]
	v_mfma_f32_16x16x32_bf16 v[116:119], v[64:67], v[168:171], v[116:119]
	v_mfma_f32_16x16x32_bf16 v[108:111], v[136:139], v[168:171], v[108:111]
	v_mfma_f32_16x16x32_bf16 v[100:103], v[64:67], v[176:179], v[100:103]
	v_mfma_f32_16x16x32_bf16 v[92:95], v[136:139], v[176:179], v[92:95]
	v_mfma_f32_16x16x32_bf16 v[84:87], v[64:67], v[184:187], v[84:87]
	v_mfma_f32_16x16x32_bf16 v[76:79], v[136:139], v[184:187], v[76:79]
	v_mfma_f32_16x16x32_bf16 v[132:135], v[68:71], v[164:167], v[132:135]
	v_mfma_f32_16x16x32_bf16 v[128:131], v[140:143], v[164:167], v[128:131]
	v_mfma_f32_16x16x32_bf16 v[116:119], v[68:71], v[172:175], v[116:119]
	v_mfma_f32_16x16x32_bf16 v[108:111], v[140:143], v[172:175], v[108:111]
	v_mfma_f32_16x16x32_bf16 v[100:103], v[68:71], v[180:183], v[100:103]
	v_mfma_f32_16x16x32_bf16 v[92:95], v[140:143], v[180:183], v[92:95]
	v_mfma_f32_16x16x32_bf16 v[84:87], v[68:71], v[188:191], v[84:87]
	v_mfma_f32_16x16x32_bf16 v[76:79], v[140:143], v[188:191], v[76:79]
	v_mfma_f32_16x16x32_bf16 v[124:127], v[144:147], v[160:163], v[124:127]
	v_mfma_f32_16x16x32_bf16 v[120:123], v[152:155], v[160:163], v[120:123]
	v_mfma_f32_16x16x32_bf16 v[112:115], v[144:147], v[168:171], v[112:115]
	v_mfma_f32_16x16x32_bf16 v[104:107], v[152:155], v[168:171], v[104:107]
	v_mfma_f32_16x16x32_bf16 v[96:99], v[144:147], v[176:179], v[96:99]
	v_mfma_f32_16x16x32_bf16 v[88:91], v[152:155], v[176:179], v[88:91]
	v_mfma_f32_16x16x32_bf16 v[80:83], v[144:147], v[184:187], v[80:83]
	v_mfma_f32_16x16x32_bf16 v[72:75], v[152:155], v[184:187], v[72:75]
	v_mfma_f32_16x16x32_bf16 v[124:127], v[148:151], v[164:167], v[124:127]
	v_mfma_f32_16x16x32_bf16 v[120:123], v[156:159], v[164:167], v[120:123]
	v_mfma_f32_16x16x32_bf16 v[112:115], v[148:151], v[172:175], v[112:115]
	v_mfma_f32_16x16x32_bf16 v[104:107], v[156:159], v[172:175], v[104:107]
	v_mfma_f32_16x16x32_bf16 v[96:99], v[148:151], v[180:183], v[96:99]
	v_mfma_f32_16x16x32_bf16 v[88:91], v[156:159], v[180:183], v[88:91]
	v_mfma_f32_16x16x32_bf16 v[80:83], v[148:151], v[188:191], v[80:83]
	v_mfma_f32_16x16x32_bf16 v[72:75], v[156:159], v[188:191], v[72:75]
	s_barrier
; #define PG8_STAGE(bufoff, gbase, voff) do { _Pragma("unroll") for (int _i = 0; _i < 2; ++_i) \
;         __builtin_amdgcn_global_load_lds((const unsigned*)((const char*)(gbase) + (voff)[_i]), (PG8_LAS unsigned*)(lds + (bufoff) + ldsw + _i * 8192), 16, 0, 0); } while (0)
; #define PG8_LDA(dst, b, h) do { _Pragma("unroll") for (int m = 0; m < 4; ++m) _Pragma("unroll") for (int k = 0; k < 2; ++k) dst[m][k] = *(const PG8_LAS bf16x8*)(lds + PG8_SA(b, h) + aoff + m * 2048 + k * 1024); } while (0)
; #define PG8_LDB(dst, b, h) do { _Pragma("unroll") for (int n = 0; n < 2; ++n) _Pragma("unroll") for (int k = 0; k < 2; ++k) dst[n][k] = *(const PG8_LAS bf16x8*)(lds + PG8_SB(b, h) + boff + n * 2048 + k * 1024); } while (0)
; #define PG8_MMA(ai, bj, At, Bt) do { __builtin_amdgcn_s_setprio(1); _Pragma("unroll") for (int m = 0; m < 4; ++m) _Pragma("unroll") for (int n = 0; n < 2; ++n) _Pragma("unroll") for (int k = 0; k < 2; ++k) \
;         acc[ai][bj][m][n] = __builtin_amdgcn_mfma_f32_16x16x32_bf16(Bt[n][k], At[m][k], acc[ai][bj][m][n], 0, 0, 0); __builtin_amdgcn_s_setprio(0); } while (0)
; #define PG8_WAIT_V(n) asm volatile("s_waitcnt vmcnt(" #n ")" ::: "memory")
; #define PG8_WAIT_L(n) asm volatile("s_waitcnt lgkmcnt(" #n ")" ::: "memory")
; #define PG8_BAR __builtin_amdgcn_s_barrier()
; #define PG8_SCHED __builtin_amdgcn_sched_barrier(0)
; template <class Epi, class Sched, bool ALIGN_EPI = false, bool SP2 = false>
; __device__ __forceinline__ void gemm_phase(PG8_LAS unsigned char* lds, const Gemm g, const Sched& S, const Epi& E, const int wave0) {
;     ...
;             PG8_LDA(At, 0, 1); PG8_STAGE(PG8_SB(0, 0), b2, voffB); PG8_STAGE(PG8_SB(0, 1), b2 + hstep, voffB); PG8_STAGE(PG8_SA(0, 0), a2, voffA);
;             PG8_WAIT_V(8); PG8_WAIT_L(0); PG8_BAR; PG8_MMA(1, 0, At, B0); PG8_MMA(1, 1, At, B1); PG8_BAR; PG8_SCHED;
;             PG8_LDB(B0, 1, 0); PG8_LDB(B1, 1, 1); PG8_SCHED; PG8_LDA(At, 1, 0); PG8_STAGE(PG8_SA(0, 1), a2 + hstep, voffA);
;             PG8_WAIT_V(8); PG8_WAIT_L(0); PG8_BAR; PG8_MMA(0, 0, At, B0); PG8_MMA(0, 1, At, B1); PG8_BAR; PG8_SCHED;
	s_add_i32 s18, s64, s95
	s_mov_b32 m0, s18
	ds_read_b128 v[160:163], v245 offset:16384
	ds_read_b128 v[164:167], v245 offset:17408
	ds_read_b128 v[168:171], v245 offset:18432
	ds_read_b128 v[172:175], v245 offset:19456
	ds_read_b128 v[176:179], v245 offset:20480
	ds_read_b128 v[180:183], v245 offset:21504
	ds_read_b128 v[184:187], v245 offset:22528
	ds_read_b128 v[188:191], v245 offset:23552
	global_load_lds_dwordx4 v218, s[56:57]
	s_add_i32 m0, s18, 0x2000
	s_add_u32 s18, s56, 0x40000
	s_addc_u32 s19, s57, 0
	s_add_i32 s64, s65, s95
	global_load_lds_dwordx4 v222, s[56:57]
	s_mov_b32 m0, s64
	s_nop 0
	global_load_lds_dwordx4 v218, s[18:19]
	s_add_i32 m0, s64, 0x2000
	s_nop 0
	global_load_lds_dwordx4 v222, s[18:19]
	s_mov_b32 m0, s33
	s_nop 0
	global_load_lds_dwordx4 v216, s[58:59]
	s_mov_b32 m0, s82
	s_nop 0
	global_load_lds_dwordx4 v220, s[58:59]
	s_waitcnt vmcnt(8)
	s_waitcnt lgkmcnt(0)
	s_barrier
	v_mfma_f32_16x16x32_bf16 v[60:63], v[64:67], v[160:163], v[60:63]
	v_mfma_f32_16x16x32_bf16 v[52:55], v[136:139], v[160:163], v[52:55]
	v_mfma_f32_16x16x32_bf16 v[44:47], v[64:67], v[168:171], v[44:47]
	v_mfma_f32_16x16x32_bf16 v[36:39], v[136:139], v[168:171], v[36:39]
	v_mfma_f32_16x16x32_bf16 v[28:31], v[64:67], v[176:179], v[28:31]
	v_mfma_f32_16x16x32_bf16 v[20:23], v[136:139], v[176:179], v[20:23]
	v_mfma_f32_16x16x32_bf16 v[12:15], v[64:67], v[184:187], v[12:15]
	v_mfma_f32_16x16x32_bf16 v[4:7], v[136:139], v[184:187], v[4:7]
	v_mfma_f32_16x16x32_bf16 v[60:63], v[68:71], v[164:167], v[60:63]
	v_mfma_f32_16x16x32_bf16 v[52:55], v[140:143], v[164:167], v[52:55]
	v_mfma_f32_16x16x32_bf16 v[44:47], v[68:71], v[172:175], v[44:47]
	v_mfma_f32_16x16x32_bf16 v[36:39], v[140:143], v[172:175], v[36:39]
	v_mfma_f32_16x16x32_bf16 v[28:31], v[68:71], v[180:183], v[28:31]
	v_mfma_f32_16x16x32_bf16 v[20:23], v[140:143], v[180:183], v[20:23]
	v_mfma_f32_16x16x32_bf16 v[12:15], v[68:71], v[188:191], v[12:15]
	v_mfma_f32_16x16x32_bf16 v[4:7], v[140:143], v[188:191], v[4:7]
	v_mfma_f32_16x16x32_bf16 v[56:59], v[144:147], v[160:163], v[56:59]
	v_mfma_f32_16x16x32_bf16 v[48:51], v[152:155], v[160:163], v[48:51]
	v_mfma_f32_16x16x32_bf16 v[40:43], v[144:147], v[168:171], v[40:43]
	v_mfma_f32_16x16x32_bf16 v[32:35], v[152:155], v[168:171], v[32:35]
	v_mfma_f32_16x16x32_bf16 v[24:27], v[144:147], v[176:179], v[24:27]
	v_mfma_f32_16x16x32_bf16 v[16:19], v[152:155], v[176:179], v[16:19]
	v_mfma_f32_16x16x32_bf16 v[8:11], v[144:147], v[184:187], v[8:11]
	v_mfma_f32_16x16x32_bf16 v[0:3], v[152:155], v[184:187], v[0:3]
	v_mfma_f32_16x16x32_bf16 v[56:59], v[148:151], v[164:167], v[56:59]
	v_mfma_f32_16x16x32_bf16 v[48:51], v[156:159], v[164:167], v[48:51]
	v_mfma_f32_16x16x32_bf16 v[40:43], v[148:151], v[172:175], v[40:43]
	v_mfma_f32_16x16x32_bf16 v[32:35], v[156:159], v[172:175], v[32:35]
	v_mfma_f32_16x16x32_bf16 v[24:27], v[148:151], v[180:183], v[24:27]
	v_mfma_f32_16x16x32_bf16 v[16:19], v[156:159], v[180:183], v[16:19]
	v_mfma_f32_16x16x32_bf16 v[8:11], v[148:151], v[188:191], v[8:11]
	v_mfma_f32_16x16x32_bf16 v[0:3], v[156:159], v[188:191], v[0:3]
	s_barrier
	s_add_i32 s64, 0, 0x18000
	s_add_i32 s65, 0, 0x1c000
	v_add_u32_e32 v140, s64, v247
	v_add_u32_e32 v156, s65, v247
	ds_read_b128 v[64:67], v140
	ds_read_b128 v[68:71], v140 offset:1024
	ds_read_b128 v[136:139], v140 offset:2048
	ds_read_b128 v[140:143], v140 offset:3072
	ds_read_b128 v[144:147], v156
	ds_read_b128 v[148:151], v156 offset:1024
	ds_read_b128 v[152:155], v156 offset:2048
	ds_read_b128 v[156:159], v156 offset:3072
	s_add_u32 s18, s58, 0x40000
	s_addc_u32 s19, s59, 0
	s_mov_b32 m0, s16
	ds_read_b128 v[160:163], v245 offset:32768
	ds_read_b128 v[164:167], v245 offset:33792
	ds_read_b128 v[168:171], v245 offset:34816
	ds_read_b128 v[172:175], v245 offset:35840
	ds_read_b128 v[176:179], v245 offset:36864
	ds_read_b128 v[180:183], v245 offset:37888
	ds_read_b128 v[184:187], v245 offset:38912
	ds_read_b128 v[188:191], v245 offset:39936
	global_load_lds_dwordx4 v216, s[18:19]
	s_mov_b32 m0, s83
	s_nop 0
	global_load_lds_dwordx4 v220, s[18:19]
	s_waitcnt vmcnt(8)
	s_waitcnt lgkmcnt(0)
	s_barrier
	v_mfma_f32_16x16x32_bf16 v[132:135], v[64:67], v[160:163], v[132:135]
	v_mfma_f32_16x16x32_bf16 v[128:131], v[136:139], v[160:163], v[128:131]
	v_mfma_f32_16x16x32_bf16 v[116:119], v[64:67], v[168:171], v[116:119]
	v_mfma_f32_16x16x32_bf16 v[108:111], v[136:139], v[168:171], v[108:111]
	v_mfma_f32_16x16x32_bf16 v[100:103], v[64:67], v[176:179], v[100:103]
	v_mfma_f32_16x16x32_bf16 v[92:95], v[136:139], v[176:179], v[92:95]
	v_mfma_f32_16x16x32_bf16 v[84:87], v[64:67], v[184:187], v[84:87]
	v_mfma_f32_16x16x32_bf16 v[76:79], v[136:139], v[184:187], v[76:79]
	v_mfma_f32_16x16x32_bf16 v[132:135], v[68:71], v[164:167], v[132:135]
	v_mfma_f32_16x16x32_bf16 v[128:131], v[140:143], v[164:167], v[128:131]
	v_mfma_f32_16x16x32_bf16 v[116:119], v[68:71], v[172:175], v[116:119]
	v_mfma_f32_16x16x32_bf16 v[108:111], v[140:143], v[172:175], v[108:111]
	v_mfma_f32_16x16x32_bf16 v[100:103], v[68:71], v[180:183], v[100:103]
	v_mfma_f32_16x16x32_bf16 v[92:95], v[140:143], v[180:183], v[92:95]
	v_mfma_f32_16x16x32_bf16 v[84:87], v[68:71], v[188:191], v[84:87]
	v_mfma_f32_16x16x32_bf16 v[76:79], v[140:143], v[188:191], v[76:79]
	v_mfma_f32_16x16x32_bf16 v[124:127], v[144:147], v[160:163], v[124:127]
	v_mfma_f32_16x16x32_bf16 v[120:123], v[152:155], v[160:163], v[120:123]
	v_mfma_f32_16x16x32_bf16 v[112:115], v[144:147], v[168:171], v[112:115]
	v_mfma_f32_16x16x32_bf16 v[104:107], v[152:155], v[168:171], v[104:107]
	v_mfma_f32_16x16x32_bf16 v[96:99], v[144:147], v[176:179], v[96:99]
	v_mfma_f32_16x16x32_bf16 v[88:91], v[152:155], v[176:179], v[88:91]
	v_mfma_f32_16x16x32_bf16 v[80:83], v[144:147], v[184:187], v[80:83]
	v_mfma_f32_16x16x32_bf16 v[72:75], v[152:155], v[184:187], v[72:75]
	v_mfma_f32_16x16x32_bf16 v[124:127], v[148:151], v[164:167], v[124:127]
	v_mfma_f32_16x16x32_bf16 v[120:123], v[156:159], v[164:167], v[120:123]
	v_mfma_f32_16x16x32_bf16 v[112:115], v[148:151], v[172:175], v[112:115]
	v_mfma_f32_16x16x32_bf16 v[104:107], v[156:159], v[172:175], v[104:107]
	v_mfma_f32_16x16x32_bf16 v[96:99], v[148:151], v[180:183], v[96:99]
	v_mfma_f32_16x16x32_bf16 v[88:91], v[156:159], v[180:183], v[88:91]
	v_mfma_f32_16x16x32_bf16 v[80:83], v[148:151], v[188:191], v[80:83]
	v_mfma_f32_16x16x32_bf16 v[72:75], v[156:159], v[188:191], v[72:75]
	s_barrier
; #define PG8_WAIT_V(n) asm volatile("s_waitcnt vmcnt(" #n ")" ::: "memory")
; template <class Epi, class Sched, bool ALIGN_EPI = false, bool SP2 = false>
; __device__ __forceinline__ void gemm_phase(PG8_LAS unsigned char* lds, const Gemm g, const Sched& S, const Epi& E, const int wave0) {
;     ...
;             PG8_LDA(At, 1, 1); PG8_STAGE(PG8_SB(1, 0), b3, voffB); PG8_STAGE(PG8_SB(1, 1), b3 + hstep, voffB); PG8_STAGE(PG8_SA(1, 0), a3, voffA);
;             PG8_WAIT_V(8); PG8_WAIT_L(0); PG8_BAR; PG8_MMA(1, 0, At, B0); PG8_MMA(1, 1, At, B1); PG8_BAR; PG8_SCHED;
;             } else {
;             PG8_LDB(B0, 0, 0); PG8_SCHED; PG8_LDA(At, 0, 0); PG8_STAGE(PG8_SA(1, 1), a1 + hstep, voffA);
;             PG8_WAIT_L(8); PG8_BAR; PG8_WAIT_L(0); PG8_MMA(0, 0, At, B0); PG8_BAR; PG8_SCHED;
;             PG8_LDB(B1, 0, 1); PG8_STAGE(PG8_SB(0, 0), b2, voffB);
;             PG8_BAR; PG8_WAIT_L(0); PG8_MMA(0, 1, At, B1); PG8_BAR;
;             PG8_LDA(At, 0, 1); PG8_STAGE(PG8_SA(0, 0), a2, voffA);
;             PG8_BAR; PG8_WAIT_L(0); PG8_MMA(1, 0, At, B0); PG8_BAR; PG8_SCHED;
;             PG8_STAGE(PG8_SB(0, 1), b2 + hstep, voffB);
;             PG8_WAIT_V(6); PG8_BAR; PG8_MMA(1, 1, At, B1); PG8_BAR;
;             PG8_LDB(B0, 1, 0); PG8_SCHED; PG8_LDA(At, 1, 0); PG8_STAGE(PG8_SA(0, 1), a2 + hstep, voffA);
;             PG8_WAIT_L(8); PG8_BAR; PG8_WAIT_L(0); PG8_MMA(0, 0, At, B0); PG8_BAR; PG8_SCHED;
;             PG8_LDB(B1, 1, 1); PG8_STAGE(PG8_SB(1, 0), b3, voffB);
;             PG8_BAR; PG8_WAIT_L(0); PG8_MMA(0, 1, At, B1); PG8_BAR;
;             PG8_LDA(At, 1, 1); PG8_STAGE(PG8_SA(1, 0), a3, voffA);
;             PG8_BAR; PG8_WAIT_L(0); PG8_MMA(1, 0, At, B0); PG8_BAR; PG8_SCHED;
;             PG8_STAGE(PG8_SB(1, 1), b3 + hstep, voffB);
;             PG8_WAIT_V(6); PG8_BAR; PG8_MMA(1, 1, At, B1); PG8_BAR;
;             }
;         }
;         if constexpr (ALIGN_EPI) { if (wr == 0) PG8_BAR; }
;     __device__ __forceinline__ void operator()(const pg8::f32x4 (&acc)[2][2][4][2], const pg8::Unit& u, int wr, int wc, int fr, int fq) const {
;     ...
;         } else if (kind == EK_BF16 && PERM) {
; #pragma unroll
;             for (int bj = 0; bj < 2; ++bj) {
;                 const int c = colb + 128 * bj;
;                 if (c < ncols) {
; #pragma unroll
;                     for (int ai = 0; ai < 2; ++ai)
; #pragma unroll
;                         for (int m = 0; m < 4; ++m) {
	s_add_i32 s18, s64, s95
	s_add_i32 m0, s18, 0xffffff80
	ds_read_b128 v[160:163], v245 offset:49152
	ds_read_b128 v[164:167], v245 offset:50176
	ds_read_b128 v[168:171], v245 offset:51200
	ds_read_b128 v[172:175], v245 offset:52224
	ds_read_b128 v[176:179], v245 offset:53248
	ds_read_b128 v[180:183], v245 offset:54272
	ds_read_b128 v[184:187], v245 offset:55296
	ds_read_b128 v[188:191], v245 offset:56320
	global_load_lds_dwordx4 v218, s[56:57] offset:128
	s_add_i32 m0, s18, 0x1f80
	s_add_u32 s18, s56, 0x40080
	s_addc_u32 s19, s57, 0
	global_load_lds_dwordx4 v222, s[56:57] offset:128
	s_add_i32 s56, s65, s95
	s_mov_b32 m0, s56
	s_nop 0
	global_load_lds_dwordx4 v218, s[18:19]
	s_add_i32 m0, s56, 0x2000
	s_nop 0
	global_load_lds_dwordx4 v222, s[18:19]
	s_add_i32 m0, s17, 0xffffff80
	s_nop 0
	global_load_lds_dwordx4 v216, s[58:59] offset:128
	s_add_i32 m0, s23, 0xffffff80
	s_nop 0
	global_load_lds_dwordx4 v220, s[58:59] offset:128
	s_waitcnt vmcnt(8)
	s_waitcnt lgkmcnt(0)
	s_barrier
	v_mfma_f32_16x16x32_bf16 v[60:63], v[64:67], v[160:163], v[60:63]
	v_mfma_f32_16x16x32_bf16 v[52:55], v[136:139], v[160:163], v[52:55]
	v_mfma_f32_16x16x32_bf16 v[44:47], v[64:67], v[168:171], v[44:47]
	v_mfma_f32_16x16x32_bf16 v[36:39], v[136:139], v[168:171], v[36:39]
	v_mfma_f32_16x16x32_bf16 v[28:31], v[64:67], v[176:179], v[28:31]
	v_mfma_f32_16x16x32_bf16 v[20:23], v[136:139], v[176:179], v[20:23]
	v_mfma_f32_16x16x32_bf16 v[12:15], v[64:67], v[184:187], v[12:15]
	v_mfma_f32_16x16x32_bf16 v[4:7], v[136:139], v[184:187], v[4:7]
	v_mfma_f32_16x16x32_bf16 v[60:63], v[68:71], v[164:167], v[60:63]
	v_mfma_f32_16x16x32_bf16 v[52:55], v[140:143], v[164:167], v[52:55]
	v_mfma_f32_16x16x32_bf16 v[44:47], v[68:71], v[172:175], v[44:47]
	v_mfma_f32_16x16x32_bf16 v[36:39], v[140:143], v[172:175], v[36:39]
	v_mfma_f32_16x16x32_bf16 v[28:31], v[68:71], v[180:183], v[28:31]
	v_mfma_f32_16x16x32_bf16 v[20:23], v[140:143], v[180:183], v[20:23]
	v_mfma_f32_16x16x32_bf16 v[12:15], v[68:71], v[188:191], v[12:15]
	v_mfma_f32_16x16x32_bf16 v[4:7], v[140:143], v[188:191], v[4:7]
	v_mfma_f32_16x16x32_bf16 v[56:59], v[144:147], v[160:163], v[56:59]
	v_mfma_f32_16x16x32_bf16 v[48:51], v[152:155], v[160:163], v[48:51]
	v_mfma_f32_16x16x32_bf16 v[40:43], v[144:147], v[168:171], v[40:43]
	v_mfma_f32_16x16x32_bf16 v[32:35], v[152:155], v[168:171], v[32:35]
	v_mfma_f32_16x16x32_bf16 v[24:27], v[144:147], v[176:179], v[24:27]
	v_mfma_f32_16x16x32_bf16 v[16:19], v[152:155], v[176:179], v[16:19]
	v_mfma_f32_16x16x32_bf16 v[8:11], v[144:147], v[184:187], v[8:11]
	v_mfma_f32_16x16x32_bf16 v[0:3], v[152:155], v[184:187], v[0:3]
	v_mfma_f32_16x16x32_bf16 v[56:59], v[148:151], v[164:167], v[56:59]
	v_mfma_f32_16x16x32_bf16 v[48:51], v[156:159], v[164:167], v[48:51]
	v_mfma_f32_16x16x32_bf16 v[40:43], v[148:151], v[172:175], v[40:43]
	v_mfma_f32_16x16x32_bf16 v[32:35], v[156:159], v[172:175], v[32:35]
	v_mfma_f32_16x16x32_bf16 v[24:27], v[148:151], v[180:183], v[24:27]
	v_mfma_f32_16x16x32_bf16 v[16:19], v[156:159], v[180:183], v[16:19]
	v_mfma_f32_16x16x32_bf16 v[8:11], v[148:151], v[188:191], v[8:11]
	v_mfma_f32_16x16x32_bf16 v[0:3], v[156:159], v[188:191], v[0:3]
	s_barrier
	s_add_i32 s63, s63, 2
	s_add_u32 s10, s10, 0x100
	s_addc_u32 s11, s11, 0
	s_add_u32 s61, s61, 0x100
	s_addc_u32 s62, s62, 0
	s_cmp_gt_u32 s63, 13
	s_cbranch_scc0 .LBB0_1140
	s_and_b64 vcc, exec, s[66:67]
	s_cbranch_vccz .LBB0_1143
	s_barrier
.LBB0_1143:
	s_setprio 0
	v_mov_b32_e32 v64, v192
	v_mov_b32_e32 v65, v193
	v_mov_b32_e32 v66, v194
	v_mov_b32_e32 v67, v195
	v_mov_b32_e32 v68, v196
	v_mov_b32_e32 v69, v197
	v_mov_b32_e32 v70, v198
	v_mov_b32_e32 v71, v199
	v_mov_b32_e32 v136, v200
	v_mov_b32_e32 v137, v201
	v_mov_b32_e32 v138, v202
	v_mov_b32_e32 v139, v203
	v_lshl_add_u32 v228, s8, 8, v252
	s_mov_b64 s[8:9], -1
	v_readfirstlane_b32 s47, v192
	s_cmp_lt_i32 s47, 1
	s_cbranch_scc1 .LBB0_1235
	v_lshl_or_b32 v230, s54, 8, v248
	s_cmp_lt_i32 s47, 2
	s_cbranch_scc1 .LBB0_1184
	s_cmp_eq_u32 s47, 2
	s_cbranch_scc0 .LBB0_1183
	v_and_b32_e32 v64, 4, v67
	v_cmp_ne_u32_e64 s[8:9], 0, v64
	v_cmp_lt_i32_e32 vcc, v230, v66
	s_nop 0
	v_cndmask_b32_e64 v64, 0, 1, s[8:9]
	v_cmp_ne_u32_e64 s[8:9], 1, v64
	s_and_saveexec_b64 s[10:11], vcc
	s_cbranch_execz .LBB0_1164
	v_ashrrev_i32_e32 v229, 31, v228
	v_mov_b64_e32 v[142:143], v[134:135]
	v_mov_b64_e32 v[146:147], v[130:131]
	s_and_b64 vcc, exec, s[8:9]
	v_lshl_add_u64 v[150:151], v[228:229], 2, v[136:137]
	v_mov_b64_e32 v[140:141], v[132:133]
	v_mov_b64_e32 v[144:145], v[128:129]
	s_cbranch_vccnz .Lepi_pre_skip_1
	global_load_dword v152, v[150:151], off
	global_load_dword v153, v[150:151], off offset:64
	global_load_dword v154, v[150:151], off offset:128
	global_load_dword v155, v[150:151], off offset:192
	global_load_dword v156, v[150:151], off offset:512
	global_load_dword v157, v[150:151], off offset:576
	global_load_dword v158, v[150:151], off offset:640
	global_load_dword v159, v[150:151], off offset:704
	s_waitcnt vmcnt(0)
